# in-proj epilogue: hand-specialised straight-line paths for wave-uniform simple column types (plain, SiLU, fp16, transposed, gate); rope/qk-norm groups keep the generic path
# speedup vs baseline: 1.2987x; 1.0089x over previous
; #define GCOMPUTE(AS, BS) GCOMPUTE_KS(AS, BS, 0) GCOMPUTE_KS(AS, BS, 1)
; template <int EPI>
; DI void gemm_phase(const P& p, int l, const u16* __restrict__ A, const u16* __restrict__ Bt, int mpx, char* lds) {
;     ...
;     GCOMPUTE(As0, Bs0)
;     __builtin_amdgcn_sched_barrier(0);
;   }
;   __syncthreads();
;   __builtin_amdgcn_sched_barrier(0);
;   GCOMPUTE(As1, Bs1)
;   __builtin_amdgcn_sched_barrier(0);
.Lgemm_in_exit:
	v_mfma_f32_16x16x32_bf16 v[102:105], v[246:249], v[162:165], v[102:105]
	v_mfma_f32_16x16x32_bf16 v[106:109], v[246:249], v[166:169], v[106:109]
	v_mfma_f32_16x16x32_bf16 v[110:113], v[246:249], v[170:173], v[110:113]
	v_mfma_f32_16x16x32_bf16 v[114:117], v[246:249], v[174:177], v[114:117]
	v_mfma_f32_16x16x32_bf16 v[118:121], v[250:253], v[162:165], v[118:121]
	v_mfma_f32_16x16x32_bf16 v[122:125], v[250:253], v[166:169], v[122:125]
	v_mfma_f32_16x16x32_bf16 v[126:129], v[250:253], v[170:173], v[126:129]
	v_mfma_f32_16x16x32_bf16 v[2:5], v[250:253], v[174:177], v[2:5]
	s_barrier
	ds_read_b128 v[162:165], v199
	ds_read_b128 v[166:169], v198
	ds_read_b128 v[170:173], v198 offset:2048
	ds_read_b128 v[174:177], v198 offset:4096
	ds_read_b128 v[178:181], v198 offset:6144
	s_waitcnt lgkmcnt(3)
	v_mfma_f32_16x16x32_bf16 v[6:9], v[162:165], v[166:169], v[6:9]
	s_waitcnt lgkmcnt(2)
	v_mfma_f32_16x16x32_bf16 v[10:13], v[162:165], v[170:173], v[10:13]
	s_waitcnt lgkmcnt(1)
	v_mfma_f32_16x16x32_bf16 v[14:17], v[162:165], v[174:177], v[14:17]
	s_waitcnt lgkmcnt(0)
	v_mfma_f32_16x16x32_bf16 v[18:21], v[162:165], v[178:181], v[18:21]
	ds_read_b128 v[162:165], v199 offset:2048
	s_waitcnt lgkmcnt(0)
	v_mfma_f32_16x16x32_bf16 v[22:25], v[162:165], v[166:169], v[22:25]
	v_mfma_f32_16x16x32_bf16 v[26:29], v[162:165], v[170:173], v[26:29]
	v_mfma_f32_16x16x32_bf16 v[30:33], v[162:165], v[174:177], v[30:33]
	v_mfma_f32_16x16x32_bf16 v[34:37], v[162:165], v[178:181], v[34:37]
	ds_read_b128 v[162:165], v199 offset:4096
	s_waitcnt lgkmcnt(0)
	v_mfma_f32_16x16x32_bf16 v[38:41], v[162:165], v[166:169], v[38:41]
	v_mfma_f32_16x16x32_bf16 v[42:45], v[162:165], v[170:173], v[42:45]
	v_mfma_f32_16x16x32_bf16 v[46:49], v[162:165], v[174:177], v[46:49]
	v_mfma_f32_16x16x32_bf16 v[50:53], v[162:165], v[178:181], v[50:53]
	ds_read_b128 v[162:165], v199 offset:6144
	s_waitcnt lgkmcnt(0)
	v_mfma_f32_16x16x32_bf16 v[54:57], v[162:165], v[166:169], v[54:57]
	v_mfma_f32_16x16x32_bf16 v[58:61], v[162:165], v[170:173], v[58:61]
	v_mfma_f32_16x16x32_bf16 v[62:65], v[162:165], v[174:177], v[62:65]
	v_mfma_f32_16x16x32_bf16 v[66:69], v[162:165], v[178:181], v[66:69]
	ds_read_b128 v[162:165], v199 offset:8192
	s_waitcnt lgkmcnt(0)
	v_mfma_f32_16x16x32_bf16 v[182:185], v[162:165], v[166:169], v[70:73]
	s_nop 2
	ds_read_b128 v[70:73], v199 offset:10240
	v_mfma_f32_16x16x32_bf16 v[186:189], v[162:165], v[170:173], v[74:77]
	s_nop 2
	ds_read_b128 v[74:77], v233
	s_waitcnt lgkmcnt(1)
	v_mfma_f32_16x16x32_bf16 v[212:215], v[70:73], v[166:169], v[86:89]
	v_mfma_f32_16x16x32_bf16 v[216:219], v[70:73], v[170:173], v[90:93]
	v_mfma_f32_16x16x32_bf16 v[220:223], v[70:73], v[174:177], v[94:97]
	v_mfma_f32_16x16x32_bf16 v[234:237], v[70:73], v[178:181], v[98:101]
	ds_read_b128 v[70:73], v199 offset:12288
	s_waitcnt lgkmcnt(0)
	v_mfma_f32_16x16x32_bf16 v[238:241], v[70:73], v[166:169], v[102:105]
	v_mfma_f32_16x16x32_bf16 v[242:245], v[70:73], v[170:173], v[106:109]
	v_mfma_f32_16x16x32_bf16 v[246:249], v[70:73], v[174:177], v[110:113]
	v_mfma_f32_16x16x32_bf16 v[250:253], v[70:73], v[178:181], v[114:117]
	ds_read_b128 v[70:73], v199 offset:14336
	v_mfma_f32_16x16x32_bf16 v[190:193], v[162:165], v[174:177], v[78:81]
	v_mfma_f32_16x16x32_bf16 v[162:165], v[162:165], v[178:181], v[82:85]
	s_waitcnt lgkmcnt(0)
	v_mfma_f32_16x16x32_bf16 v[178:181], v[70:73], v[178:181], v[2:5]
	s_nop 2
	ds_read_b128 v[2:5], v200
	v_mfma_f32_16x16x32_bf16 v[174:177], v[70:73], v[174:177], v[126:129]
	s_waitcnt lgkmcnt(0)
	v_mfma_f32_16x16x32_bf16 v[126:129], v[74:77], v[2:5], v[6:9]
	s_nop 2
	ds_read_b128 v[6:9], v200 offset:2048
	v_mfma_f32_16x16x32_bf16 v[170:173], v[70:73], v[170:173], v[122:125]
	s_waitcnt lgkmcnt(0)
	v_mfma_f32_16x16x32_bf16 v[122:125], v[74:77], v[6:9], v[10:13]
	s_nop 2
	ds_read_b128 v[10:13], v200 offset:4096
	v_mfma_f32_16x16x32_bf16 v[166:169], v[70:73], v[166:169], v[118:121]
	s_waitcnt lgkmcnt(0)
	v_mfma_f32_16x16x32_bf16 v[118:121], v[74:77], v[10:13], v[14:17]
	s_nop 2
	ds_read_b128 v[14:17], v200 offset:6144
	s_waitcnt lgkmcnt(0)
	v_mfma_f32_16x16x32_bf16 v[114:117], v[74:77], v[14:17], v[18:21]
	s_nop 2
	ds_read_b128 v[18:21], v233 offset:2048
	s_waitcnt lgkmcnt(0)
	v_mfma_f32_16x16x32_bf16 v[110:113], v[18:21], v[2:5], v[22:25]
	v_mfma_f32_16x16x32_bf16 v[106:109], v[18:21], v[6:9], v[26:29]
	v_mfma_f32_16x16x32_bf16 v[102:105], v[18:21], v[10:13], v[30:33]
	v_mfma_f32_16x16x32_bf16 v[98:101], v[18:21], v[14:17], v[34:37]
	ds_read_b128 v[18:21], v233 offset:4096
	s_waitcnt lgkmcnt(0)
	v_mfma_f32_16x16x32_bf16 v[94:97], v[18:21], v[2:5], v[38:41]
	v_mfma_f32_16x16x32_bf16 v[90:93], v[18:21], v[6:9], v[42:45]
	v_mfma_f32_16x16x32_bf16 v[86:89], v[18:21], v[10:13], v[46:49]
	v_mfma_f32_16x16x32_bf16 v[82:85], v[18:21], v[14:17], v[50:53]
	ds_read_b128 v[18:21], v233 offset:6144
	s_waitcnt lgkmcnt(0)
	v_mfma_f32_16x16x32_bf16 v[78:81], v[18:21], v[2:5], v[54:57]
	v_mfma_f32_16x16x32_bf16 v[74:77], v[18:21], v[6:9], v[58:61]
	v_mfma_f32_16x16x32_bf16 v[70:73], v[18:21], v[10:13], v[62:65]
	v_mfma_f32_16x16x32_bf16 v[66:69], v[18:21], v[14:17], v[66:69]
	ds_read_b128 v[18:21], v233 offset:8192
	s_waitcnt lgkmcnt(0)
	v_mfma_f32_16x16x32_bf16 v[62:65], v[18:21], v[2:5], v[182:185]
	s_nop 2
	ds_read_b128 v[182:185], v233 offset:14336
	v_mfma_f32_16x16x32_bf16 v[58:61], v[18:21], v[6:9], v[186:189]
	v_mfma_f32_16x16x32_bf16 v[54:57], v[18:21], v[10:13], v[190:193]
	v_mfma_f32_16x16x32_bf16 v[50:53], v[18:21], v[14:17], v[162:165]
	ds_read_b128 v[18:21], v233 offset:10240
	s_waitcnt lgkmcnt(0)
	v_mfma_f32_16x16x32_bf16 v[46:49], v[18:21], v[2:5], v[212:215]
	v_mfma_f32_16x16x32_bf16 v[42:45], v[18:21], v[6:9], v[216:219]
	v_mfma_f32_16x16x32_bf16 v[38:41], v[18:21], v[10:13], v[220:223]
	v_mfma_f32_16x16x32_bf16 v[34:37], v[18:21], v[14:17], v[234:237]
	ds_read_b128 v[18:21], v233 offset:12288
	s_waitcnt lgkmcnt(0)
	v_mfma_f32_16x16x32_bf16 v[30:33], v[18:21], v[2:5], v[238:241]
	v_mfma_f32_16x16x32_bf16 v[26:29], v[18:21], v[6:9], v[242:245]
	v_mfma_f32_16x16x32_bf16 v[22:25], v[18:21], v[10:13], v[246:249]
	v_mfma_f32_16x16x32_bf16 v[18:21], v[18:21], v[14:17], v[250:253]
	v_mfma_f32_16x16x32_bf16 v[166:169], v[182:185], v[2:5], v[166:169]
	v_mfma_f32_16x16x32_bf16 v[162:165], v[182:185], v[6:9], v[170:173]
	v_mfma_f32_16x16x32_bf16 v[2:5], v[182:185], v[10:13], v[174:177]
	v_mfma_f32_16x16x32_bf16 v[6:9], v[182:185], v[14:17], v[178:181]
	s_barrier
; template <int EPI>
; DI void gemm_phase(const P& p, int l, const u16* __restrict__ A, const u16* __restrict__ Bt, int mpx, char* lds) {
;     ...
;     const int cb = n0 + wn * 64;
;     const bool isctx = m0 >= MLAT;
;     const int b = isctx ? ((m0 - MLAT) >> 8) : (m0 >> 11);
;     const int tokw = (isctx ? 2048 + ((m0 - MLAT) & 255) : (m0 & 2047)) + wm * 128;
;     u16* Tl = (u16*)(lds + 65536) + w * (64 * 72);
;     int kind = 0;
;     int tr = 0;
;     bool donorm = false;
;     if (cb >= 2816) { kind = 2; tr = 1; }
;     else if (cb < 256) tr = 1;
;     else if (cb < 512) tr = 0;
;     else if (cb < 1024) tr = 2;
;     else if (cb < 1408) { tr = 3; donorm = true; }
;     else if (cb < 1536) kind = 1;
;     else if (cb < 2048) tr = isctx ? 0 : 4;
;     else if (cb < 2304) kind = 1;
;     else if (cb < 2688) tr = isctx ? 0 : 3;
;     else kind = 1;
;     const float* gw = (cb < 1280 ? p.ga_qn : p.ga_kn) + l * 64;
;     float gv0 = 1.f, gv1 = 1.f, gv2 = 1.f, gv3 = 1.f;
;     if (donorm) { gv0 = gw[r]; gv1 = gw[16 + r]; gv2 = gw[32 + r]; gv3 = gw[48 + r]; }
;     const bool dorope = (tr == 3) && !isctx;
;     const float invf64 = exp2f(-13.287712379549449f * (float)r * (1.f / 16.f));
;     const float invf32 = exp2f(-13.287712379549449f * (float)(r & 7) * (1.f / 8.f));
;     const bool lo8 = r < 8;
;     u16* dst;
;     size_t rstride;
;     if (kind == 2) {
;       dst = p.G + (size_t)(m0 + wm * 128) * 1024 + (cb - 2816);
;       rstride = 1024;
;     } else if (kind == 1) {
;       dst = slab_ptr(p, cb >> 6, b) + tokw;
;       rstride = T;
;     } else {
;       dst = slab_ptr(p, cb >> 6, b) + (size_t)tokw * 64;
;       rstride = 64;
;     }
; #pragma unroll
;     for (int hf = 0; hf < 2; ++hf) {
; #pragma unroll
;       for (int mi = 0; mi < 4; ++mi) {
; #pragma unroll
;         for (int j = 0; j < 4; ++j) {
;           float v0 = acc[hf * 4 + mi][0][j], v1 = acc[hf * 4 + mi][1][j], v2 = acc[hf * 4 + mi][2][j], v3 = acc[hf * 4 + mi][3][j];
;           const int rowl = mi * 16 + g * 4 + j;
;           const int s = tokw + hf * 64 + rowl;
;           if (tr == 1) {
;             v0 = silu(v0); v1 = silu(v1); v2 = silu(v2); v3 = silu(v3);
;     ...
;           const unsigned u01 = pack2(v0, v1), u23 = pack2(v2, v3);
;           if (kind == 1) {
;             Tl[(0 * 16 + r) * 72 + rowl] = (u16)u01;
;             Tl[(1 * 16 + r) * 72 + rowl] = (u16)(u01 >> 16);
	s_waitcnt vmcnt(7)
	ds_write_b128 v201, v[130:133]
	s_waitcnt vmcnt(5)
	ds_write_b128 v201, v[134:137] offset:8192
	s_waitcnt vmcnt(4)
	ds_write_b128 v201, v[138:141] offset:16384
	s_waitcnt vmcnt(3)
	ds_write_b128 v201, v[142:145] offset:24576
	ds_write_b128 v201, v[146:149] offset:32768
	s_waitcnt vmcnt(2)
	ds_write_b128 v201, v[150:153] offset:40960
	s_waitcnt vmcnt(1)
	ds_write_b128 v201, v[154:157] offset:49152
	s_waitcnt vmcnt(0)
	ds_write_b128 v201, v[158:161] offset:57344
	v_readfirstlane_b32 s40, v195
	s_lshr_b32 s40, s40, 6
	s_and_b32 s41, s40, 3
	s_lshr_b32 s42, s40, 2
	s_lshr_b32 s43, s46, 6
	s_add_i32 s43, s43, s41
	s_cmp_ge_u32 s66, 0x8000
	s_cselect_b32 s67, 1, 0
	s_mov_b32 s44, 0xffff
	s_mov_b32 s45, 0
	s_bitcmp1_b64 s[44:45], s43
	s_cbranch_scc1 .Lfe_kind0
	s_mov_b32 s44, 0xc00000
	s_mov_b32 s45, 0xc0f
	s_bitcmp1_b64 s[44:45], s43
	s_cbranch_scc1 .Lfe_kind1
	s_cmp_ge_u32 s43, 44
	s_cbranch_scc1 .Lfe_kind2
	s_cmp_eq_u32 s67, 0
	s_cbranch_scc1 .Lfe_slow
	s_mov_b32 s44, 0xff000000
	s_mov_b32 s45, 0x3f0
	s_bitcmp1_b64 s[44:45], s43
	s_cbranch_scc1 .Lfe_slow
	s_branch .Lfe_slow
.Lfe_kind0:
	s_sub_u32 s68, s66, 0x8000
	s_lshr_b32 s68, s68, 8
	s_lshr_b32 s69, s66, 11
	s_and_b32 s70, s66, 0x7ff
	s_cmp_eq_u32 s67, 0
	s_cselect_b32 s68, s69, s68
	s_cselect_b32 s69, s70, 0x800
	s_lshl_b32 s70, s42, 7
	s_add_i32 s69, s69, s70
	s_mul_i32 s70, s40, 0x2400
	s_add_i32 s70, s70, s78
	v_and_b32_e32 v173, 15, v226
	v_lshrrev_b32_e32 v0, 4, v226
	v_mul_u32_u24_e32 v170, 0x240, v0
	v_lshl_add_u32 v170, v173, 1, v170
	v_add_u32_e32 v170, s70, v170
	v_lshrrev_b32_e32 v0, 3, v226
	v_and_b32_e32 v173, 7, v226
	v_mul_u32_u24_e32 v171, 0x90, v0
	v_lshl_add_u32 v171, v173, 4, v171
	v_add_u32_e32 v171, s70, v171
	v_lshlrev_b32_e32 v172, 4, v226
	s_lshl_b32 s70, s43, 4
	s_add_i32 s70, s70, s68
	s_mul_hi_u32 s71, s70, 0x48000
	s_mul_i32 s70, s70, 0x48000
	s_add_u32 s44, s18, s70
	s_addc_u32 s45, s19, s71
	s_lshl_b32 s70, s69, 7
	s_add_u32 s44, s44, s70
	s_addc_u32 s45, s45, 0
	s_cmp_lt_u32 s43, 4
	s_cbranch_scc1 .Lfe_k0_silu
	s_cmp_lt_u32 s43, 8
	s_cbranch_scc1 .Lfe_k0_plain
	s_cmp_lt_u32 s43, 16
	s_cbranch_scc1 .Lfe_k0_fp16
	s_branch .Lfe_k0_plain
.Lfe_k0_silu:
	s_add_u32 s62, s44, 0x1000
	s_addc_u32 s63, s45, 0
	v_mul_f32_e32 v174, 0xbfb8aa3b, v126
	v_mul_f32_e32 v175, 0xbfb8aa3b, v122
	v_mul_f32_e32 v176, 0xbfb8aa3b, v118
	v_mul_f32_e32 v177, 0xbfb8aa3b, v114
	v_exp_f32_e32 v174, v174
	v_exp_f32_e32 v175, v175
	v_exp_f32_e32 v176, v176
	v_exp_f32_e32 v177, v177
	v_add_f32_e32 v174, 1.0, v174
	v_add_f32_e32 v175, 1.0, v175
	v_add_f32_e32 v176, 1.0, v176
	v_add_f32_e32 v177, 1.0, v177
	v_rcp_f32_e32 v174, v174
	v_rcp_f32_e32 v175, v175
	v_rcp_f32_e32 v176, v176
	v_rcp_f32_e32 v177, v177
	v_mul_f32_e32 v174, v126, v174
	v_mul_f32_e32 v175, v122, v175
	v_mul_f32_e32 v176, v118, v176
	v_mul_f32_e32 v177, v114, v177
	v_cvt_pk_bf16_f32 v178, v174, v175
	v_cvt_pk_bf16_f32 v179, v176, v177
	ds_write_b16 v170, v178 offset:0
	ds_write_b16_d16_hi v170, v178 offset:32
	ds_write_b16 v170, v179 offset:64
	ds_write_b16_d16_hi v170, v179 offset:96
	v_mul_f32_e32 v180, 0xbfb8aa3b, v127
	v_mul_f32_e32 v181, 0xbfb8aa3b, v123
	v_mul_f32_e32 v182, 0xbfb8aa3b, v119
	v_mul_f32_e32 v183, 0xbfb8aa3b, v115
	v_exp_f32_e32 v180, v180
	v_exp_f32_e32 v181, v181
	v_exp_f32_e32 v182, v182
	v_exp_f32_e32 v183, v183
	v_add_f32_e32 v180, 1.0, v180
	v_add_f32_e32 v181, 1.0, v181
	v_add_f32_e32 v182, 1.0, v182
	v_add_f32_e32 v183, 1.0, v183
	v_rcp_f32_e32 v180, v180
	v_rcp_f32_e32 v181, v181
	v_rcp_f32_e32 v182, v182
	v_rcp_f32_e32 v183, v183
	v_mul_f32_e32 v180, v127, v180
	v_mul_f32_e32 v181, v123, v181
	v_mul_f32_e32 v182, v119, v182
	v_mul_f32_e32 v183, v115, v183
	v_cvt_pk_bf16_f32 v184, v180, v181
	v_cvt_pk_bf16_f32 v185, v182, v183
	ds_write_b16 v170, v184 offset:144
	ds_write_b16_d16_hi v170, v184 offset:176
	ds_write_b16 v170, v185 offset:208
	ds_write_b16_d16_hi v170, v185 offset:240
	v_mul_f32_e32 v186, 0xbfb8aa3b, v128
	v_mul_f32_e32 v187, 0xbfb8aa3b, v124
	v_mul_f32_e32 v188, 0xbfb8aa3b, v120
	v_mul_f32_e32 v189, 0xbfb8aa3b, v116
	v_exp_f32_e32 v186, v186
	v_exp_f32_e32 v187, v187
	v_exp_f32_e32 v188, v188
	v_exp_f32_e32 v189, v189
	v_add_f32_e32 v186, 1.0, v186
	v_add_f32_e32 v187, 1.0, v187
	v_add_f32_e32 v188, 1.0, v188
	v_add_f32_e32 v189, 1.0, v189
	v_rcp_f32_e32 v186, v186
	v_rcp_f32_e32 v187, v187
	v_rcp_f32_e32 v188, v188
	v_rcp_f32_e32 v189, v189
	v_mul_f32_e32 v186, v128, v186
	v_mul_f32_e32 v187, v124, v187
	v_mul_f32_e32 v188, v120, v188
	v_mul_f32_e32 v189, v116, v189
	v_cvt_pk_bf16_f32 v190, v186, v187
	v_cvt_pk_bf16_f32 v191, v188, v189
	ds_write_b16 v170, v190 offset:288
	ds_write_b16_d16_hi v170, v190 offset:320
	ds_write_b16 v170, v191 offset:352
	ds_write_b16_d16_hi v170, v191 offset:384
	v_mul_f32_e32 v192, 0xbfb8aa3b, v129
	v_mul_f32_e32 v193, 0xbfb8aa3b, v125
	v_mul_f32_e32 v174, 0xbfb8aa3b, v121
	v_mul_f32_e32 v175, 0xbfb8aa3b, v117
	v_exp_f32_e32 v192, v192
	v_exp_f32_e32 v193, v193
	v_exp_f32_e32 v174, v174
	v_exp_f32_e32 v175, v175
	v_add_f32_e32 v192, 1.0, v192
	v_add_f32_e32 v193, 1.0, v193
	v_add_f32_e32 v174, 1.0, v174
	v_add_f32_e32 v175, 1.0, v175
	v_rcp_f32_e32 v192, v192
	v_rcp_f32_e32 v193, v193
	v_rcp_f32_e32 v174, v174
	v_rcp_f32_e32 v175, v175
	v_mul_f32_e32 v192, v129, v192
	v_mul_f32_e32 v193, v125, v193
	v_mul_f32_e32 v174, v121, v174
	v_mul_f32_e32 v175, v117, v175
	v_cvt_pk_bf16_f32 v176, v192, v193
	v_cvt_pk_bf16_f32 v177, v174, v175
	ds_write_b16 v170, v176 offset:432
	ds_write_b16_d16_hi v170, v176 offset:464
	ds_write_b16 v170, v177 offset:496
	ds_write_b16_d16_hi v170, v177 offset:528
	v_mul_f32_e32 v178, 0xbfb8aa3b, v110
; DI float silu(float v) { return v * __builtin_amdgcn_rcpf(1.f + __builtin_amdgcn_exp2f(-1.4426950408889634f * v)); }
; template <int EPI>
; DI void gemm_phase(const P& p, int l, const u16* __restrict__ A, const u16* __restrict__ Bt, int mpx, char* lds) {
;     ...
;         for (int j = 0; j < 4; ++j) {
;           float v0 = acc[hf * 4 + mi][0][j], v1 = acc[hf * 4 + mi][1][j], v2 = acc[hf * 4 + mi][2][j], v3 = acc[hf * 4 + mi][3][j];
;           const int rowl = mi * 16 + g * 4 + j;
;           const int s = tokw + hf * 64 + rowl;
;           if (tr == 1) {
;             v0 = silu(v0); v1 = silu(v1); v2 = silu(v2); v3 = silu(v3);
;     ...
;           const unsigned u01 = pack2(v0, v1), u23 = pack2(v2, v3);
;           if (kind == 1) {
;             Tl[(0 * 16 + r) * 72 + rowl] = (u16)u01;
;             Tl[(1 * 16 + r) * 72 + rowl] = (u16)(u01 >> 16);
;             Tl[(2 * 16 + r) * 72 + rowl] = (u16)u23;
;             Tl[(3 * 16 + r) * 72 + rowl] = (u16)(u23 >> 16);
;           } else if (tr == 2) {
;             Tl[rowl * 72 + 0 * 16 + r] = f2h(v0);
;             Tl[rowl * 72 + 1 * 16 + r] = f2h(v1);
;             Tl[rowl * 72 + 2 * 16 + r] = f2h(v2);
;             Tl[rowl * 72 + 3 * 16 + r] = f2h(v3);
;           } else {
;             Tl[rowl * 72 + 0 * 16 + r] = (u16)u01;
;             Tl[rowl * 72 + 1 * 16 + r] = (u16)(u01 >> 16);
;             Tl[rowl * 72 + 2 * 16 + r] = (u16)u23;
;             Tl[rowl * 72 + 3 * 16 + r] = (u16)(u23 >> 16);
;           }
	v_mul_f32_e32 v179, 0xbfb8aa3b, v106
	v_mul_f32_e32 v180, 0xbfb8aa3b, v102
	v_mul_f32_e32 v181, 0xbfb8aa3b, v98
	v_exp_f32_e32 v178, v178
	v_exp_f32_e32 v179, v179
	v_exp_f32_e32 v180, v180
	v_exp_f32_e32 v181, v181
	v_add_f32_e32 v178, 1.0, v178
	v_add_f32_e32 v179, 1.0, v179
	v_add_f32_e32 v180, 1.0, v180
	v_add_f32_e32 v181, 1.0, v181
	v_rcp_f32_e32 v178, v178
	v_rcp_f32_e32 v179, v179
	v_rcp_f32_e32 v180, v180
	v_rcp_f32_e32 v181, v181
	v_mul_f32_e32 v178, v110, v178
	v_mul_f32_e32 v179, v106, v179
	v_mul_f32_e32 v180, v102, v180
	v_mul_f32_e32 v181, v98, v181
	v_cvt_pk_bf16_f32 v182, v178, v179
	v_cvt_pk_bf16_f32 v183, v180, v181
	ds_write_b16 v170, v182 offset:2304
	ds_write_b16_d16_hi v170, v182 offset:2336
	ds_write_b16 v170, v183 offset:2368
	ds_write_b16_d16_hi v170, v183 offset:2400
	v_mul_f32_e32 v184, 0xbfb8aa3b, v111
	v_mul_f32_e32 v185, 0xbfb8aa3b, v107
	v_mul_f32_e32 v186, 0xbfb8aa3b, v103
	v_mul_f32_e32 v187, 0xbfb8aa3b, v99
	v_exp_f32_e32 v184, v184
	v_exp_f32_e32 v185, v185
	v_exp_f32_e32 v186, v186
	v_exp_f32_e32 v187, v187
	v_add_f32_e32 v184, 1.0, v184
	v_add_f32_e32 v185, 1.0, v185
	v_add_f32_e32 v186, 1.0, v186
	v_add_f32_e32 v187, 1.0, v187
	v_rcp_f32_e32 v184, v184
	v_rcp_f32_e32 v185, v185
	v_rcp_f32_e32 v186, v186
	v_rcp_f32_e32 v187, v187
	v_mul_f32_e32 v184, v111, v184
	v_mul_f32_e32 v185, v107, v185
	v_mul_f32_e32 v186, v103, v186
	v_mul_f32_e32 v187, v99, v187
	v_cvt_pk_bf16_f32 v188, v184, v185
	v_cvt_pk_bf16_f32 v189, v186, v187
	ds_write_b16 v170, v188 offset:2448
	ds_write_b16_d16_hi v170, v188 offset:2480
	ds_write_b16 v170, v189 offset:2512
	ds_write_b16_d16_hi v170, v189 offset:2544
	v_mul_f32_e32 v190, 0xbfb8aa3b, v112
	v_mul_f32_e32 v191, 0xbfb8aa3b, v108
	v_mul_f32_e32 v192, 0xbfb8aa3b, v104
	v_mul_f32_e32 v193, 0xbfb8aa3b, v100
	v_exp_f32_e32 v190, v190
	v_exp_f32_e32 v191, v191
	v_exp_f32_e32 v192, v192
	v_exp_f32_e32 v193, v193
	v_add_f32_e32 v190, 1.0, v190
	v_add_f32_e32 v191, 1.0, v191
	v_add_f32_e32 v192, 1.0, v192
	v_add_f32_e32 v193, 1.0, v193
	v_rcp_f32_e32 v190, v190
	v_rcp_f32_e32 v191, v191
	v_rcp_f32_e32 v192, v192
	v_rcp_f32_e32 v193, v193
	v_mul_f32_e32 v190, v112, v190
	v_mul_f32_e32 v191, v108, v191
	v_mul_f32_e32 v192, v104, v192
	v_mul_f32_e32 v193, v100, v193
	v_cvt_pk_bf16_f32 v174, v190, v191
	v_cvt_pk_bf16_f32 v175, v192, v193
	ds_write_b16 v170, v174 offset:2592
	ds_write_b16_d16_hi v170, v174 offset:2624
	ds_write_b16 v170, v175 offset:2656
	ds_write_b16_d16_hi v170, v175 offset:2688
	v_mul_f32_e32 v176, 0xbfb8aa3b, v113
	v_mul_f32_e32 v177, 0xbfb8aa3b, v109
	v_mul_f32_e32 v178, 0xbfb8aa3b, v105
	v_mul_f32_e32 v179, 0xbfb8aa3b, v101
	v_exp_f32_e32 v176, v176
	v_exp_f32_e32 v177, v177
	v_exp_f32_e32 v178, v178
	v_exp_f32_e32 v179, v179
	v_add_f32_e32 v176, 1.0, v176
	v_add_f32_e32 v177, 1.0, v177
	v_add_f32_e32 v178, 1.0, v178
	v_add_f32_e32 v179, 1.0, v179
	v_rcp_f32_e32 v176, v176
	v_rcp_f32_e32 v177, v177
	v_rcp_f32_e32 v178, v178
	v_rcp_f32_e32 v179, v179
	v_mul_f32_e32 v176, v113, v176
	v_mul_f32_e32 v177, v109, v177
	v_mul_f32_e32 v178, v105, v178
	v_mul_f32_e32 v179, v101, v179
	v_cvt_pk_bf16_f32 v180, v176, v177
	v_cvt_pk_bf16_f32 v181, v178, v179
	ds_write_b16 v170, v180 offset:2736
	ds_write_b16_d16_hi v170, v180 offset:2768
	ds_write_b16 v170, v181 offset:2800
	ds_write_b16_d16_hi v170, v181 offset:2832
	v_mul_f32_e32 v182, 0xbfb8aa3b, v94
	v_mul_f32_e32 v183, 0xbfb8aa3b, v90
	v_mul_f32_e32 v184, 0xbfb8aa3b, v86
	v_mul_f32_e32 v185, 0xbfb8aa3b, v82
	v_exp_f32_e32 v182, v182
	v_exp_f32_e32 v183, v183
	v_exp_f32_e32 v184, v184
	v_exp_f32_e32 v185, v185
	v_add_f32_e32 v182, 1.0, v182
	v_add_f32_e32 v183, 1.0, v183
	v_add_f32_e32 v184, 1.0, v184
	v_add_f32_e32 v185, 1.0, v185
	v_rcp_f32_e32 v182, v182
	v_rcp_f32_e32 v183, v183
	v_rcp_f32_e32 v184, v184
	v_rcp_f32_e32 v185, v185
	v_mul_f32_e32 v182, v94, v182
	v_mul_f32_e32 v183, v90, v183
	v_mul_f32_e32 v184, v86, v184
	v_mul_f32_e32 v185, v82, v185
	v_cvt_pk_bf16_f32 v186, v182, v183
	v_cvt_pk_bf16_f32 v187, v184, v185
	ds_write_b16 v170, v186 offset:4608
	ds_write_b16_d16_hi v170, v186 offset:4640
	ds_write_b16 v170, v187 offset:4672
	ds_write_b16_d16_hi v170, v187 offset:4704
	v_mul_f32_e32 v188, 0xbfb8aa3b, v95
	v_mul_f32_e32 v189, 0xbfb8aa3b, v91
	v_mul_f32_e32 v190, 0xbfb8aa3b, v87
	v_mul_f32_e32 v191, 0xbfb8aa3b, v83
	v_exp_f32_e32 v188, v188
	v_exp_f32_e32 v189, v189
	v_exp_f32_e32 v190, v190
	v_exp_f32_e32 v191, v191
	v_add_f32_e32 v188, 1.0, v188
	v_add_f32_e32 v189, 1.0, v189
	v_add_f32_e32 v190, 1.0, v190
	v_add_f32_e32 v191, 1.0, v191
	v_rcp_f32_e32 v188, v188
	v_rcp_f32_e32 v189, v189
	v_rcp_f32_e32 v190, v190
	v_rcp_f32_e32 v191, v191
	v_mul_f32_e32 v188, v95, v188
	v_mul_f32_e32 v189, v91, v189
	v_mul_f32_e32 v190, v87, v190
	v_mul_f32_e32 v191, v83, v191
	v_cvt_pk_bf16_f32 v192, v188, v189
	v_cvt_pk_bf16_f32 v193, v190, v191
	ds_write_b16 v170, v192 offset:4752
	ds_write_b16_d16_hi v170, v192 offset:4784
	ds_write_b16 v170, v193 offset:4816
	ds_write_b16_d16_hi v170, v193 offset:4848
	v_mul_f32_e32 v174, 0xbfb8aa3b, v96
	v_mul_f32_e32 v175, 0xbfb8aa3b, v92
	v_mul_f32_e32 v176, 0xbfb8aa3b, v88
	v_mul_f32_e32 v177, 0xbfb8aa3b, v84
	v_exp_f32_e32 v174, v174
	v_exp_f32_e32 v175, v175
	v_exp_f32_e32 v176, v176
	v_exp_f32_e32 v177, v177
	v_add_f32_e32 v174, 1.0, v174
	v_add_f32_e32 v175, 1.0, v175
	v_add_f32_e32 v176, 1.0, v176
	v_add_f32_e32 v177, 1.0, v177
	v_rcp_f32_e32 v174, v174
	v_rcp_f32_e32 v175, v175
	v_rcp_f32_e32 v176, v176
	v_rcp_f32_e32 v177, v177
	v_mul_f32_e32 v174, v96, v174
	v_mul_f32_e32 v175, v92, v175
	v_mul_f32_e32 v176, v88, v176
	v_mul_f32_e32 v177, v84, v177
; DI float silu(float v) { return v * __builtin_amdgcn_rcpf(1.f + __builtin_amdgcn_exp2f(-1.4426950408889634f * v)); }
; template <int EPI>
; DI void gemm_phase(const P& p, int l, const u16* __restrict__ A, const u16* __restrict__ Bt, int mpx, char* lds) {
;     ...
;         for (int j = 0; j < 4; ++j) {
;           float v0 = acc[hf * 4 + mi][0][j], v1 = acc[hf * 4 + mi][1][j], v2 = acc[hf * 4 + mi][2][j], v3 = acc[hf * 4 + mi][3][j];
;           const int rowl = mi * 16 + g * 4 + j;
;           const int s = tokw + hf * 64 + rowl;
;           if (tr == 1) {
;             v0 = silu(v0); v1 = silu(v1); v2 = silu(v2); v3 = silu(v3);
;     ...
;           } else {
;             Tl[rowl * 72 + 0 * 16 + r] = (u16)u01;
;             Tl[rowl * 72 + 1 * 16 + r] = (u16)(u01 >> 16);
;             Tl[rowl * 72 + 2 * 16 + r] = (u16)u23;
;             Tl[rowl * 72 + 3 * 16 + r] = (u16)(u23 >> 16);
;           }
;         }
;       }
;       __builtin_amdgcn_fence(__ATOMIC_RELEASE, "wavefront");
;       u16* dh = (kind == 1) ? dst + hf * 64 : dst + (size_t)(hf * 64) * rstride;
; #pragma unroll
;       for (int i = 0; i < 8; ++i) {
;         const int c = lane + i * 64;
;         const int row = c >> 3, cc = c & 7;
;         uint4 v = *(const uint4*)&Tl[row * 72 + cc * 8];
;         *(uint4*)(dh + (size_t)row * rstride + cc * 8) = v;
;       }
	v_cvt_pk_bf16_f32 v178, v174, v175
	v_cvt_pk_bf16_f32 v179, v176, v177
	ds_write_b16 v170, v178 offset:4896
	ds_write_b16_d16_hi v170, v178 offset:4928
	ds_write_b16 v170, v179 offset:4960
	ds_write_b16_d16_hi v170, v179 offset:4992
	v_mul_f32_e32 v180, 0xbfb8aa3b, v97
	v_mul_f32_e32 v181, 0xbfb8aa3b, v93
	v_mul_f32_e32 v182, 0xbfb8aa3b, v89
	v_mul_f32_e32 v183, 0xbfb8aa3b, v85
	v_exp_f32_e32 v180, v180
	v_exp_f32_e32 v181, v181
	v_exp_f32_e32 v182, v182
	v_exp_f32_e32 v183, v183
	v_add_f32_e32 v180, 1.0, v180
	v_add_f32_e32 v181, 1.0, v181
	v_add_f32_e32 v182, 1.0, v182
	v_add_f32_e32 v183, 1.0, v183
	v_rcp_f32_e32 v180, v180
	v_rcp_f32_e32 v181, v181
	v_rcp_f32_e32 v182, v182
	v_rcp_f32_e32 v183, v183
	v_mul_f32_e32 v180, v97, v180
	v_mul_f32_e32 v181, v93, v181
	v_mul_f32_e32 v182, v89, v182
	v_mul_f32_e32 v183, v85, v183
	v_cvt_pk_bf16_f32 v184, v180, v181
	v_cvt_pk_bf16_f32 v185, v182, v183
	ds_write_b16 v170, v184 offset:5040
	ds_write_b16_d16_hi v170, v184 offset:5072
	ds_write_b16 v170, v185 offset:5104
	ds_write_b16_d16_hi v170, v185 offset:5136
	v_mul_f32_e32 v186, 0xbfb8aa3b, v78
	v_mul_f32_e32 v187, 0xbfb8aa3b, v74
	v_mul_f32_e32 v188, 0xbfb8aa3b, v70
	v_mul_f32_e32 v189, 0xbfb8aa3b, v66
	v_exp_f32_e32 v186, v186
	v_exp_f32_e32 v187, v187
	v_exp_f32_e32 v188, v188
	v_exp_f32_e32 v189, v189
	v_add_f32_e32 v186, 1.0, v186
	v_add_f32_e32 v187, 1.0, v187
	v_add_f32_e32 v188, 1.0, v188
	v_add_f32_e32 v189, 1.0, v189
	v_rcp_f32_e32 v186, v186
	v_rcp_f32_e32 v187, v187
	v_rcp_f32_e32 v188, v188
	v_rcp_f32_e32 v189, v189
	v_mul_f32_e32 v186, v78, v186
	v_mul_f32_e32 v187, v74, v187
	v_mul_f32_e32 v188, v70, v188
	v_mul_f32_e32 v189, v66, v189
	v_cvt_pk_bf16_f32 v190, v186, v187
	v_cvt_pk_bf16_f32 v191, v188, v189
	ds_write_b16 v170, v190 offset:6912
	ds_write_b16_d16_hi v170, v190 offset:6944
	ds_write_b16 v170, v191 offset:6976
	ds_write_b16_d16_hi v170, v191 offset:7008
	v_mul_f32_e32 v192, 0xbfb8aa3b, v79
	v_mul_f32_e32 v193, 0xbfb8aa3b, v75
	v_mul_f32_e32 v174, 0xbfb8aa3b, v71
	v_mul_f32_e32 v175, 0xbfb8aa3b, v67
	v_exp_f32_e32 v192, v192
	v_exp_f32_e32 v193, v193
	v_exp_f32_e32 v174, v174
	v_exp_f32_e32 v175, v175
	v_add_f32_e32 v192, 1.0, v192
	v_add_f32_e32 v193, 1.0, v193
	v_add_f32_e32 v174, 1.0, v174
	v_add_f32_e32 v175, 1.0, v175
	v_rcp_f32_e32 v192, v192
	v_rcp_f32_e32 v193, v193
	v_rcp_f32_e32 v174, v174
	v_rcp_f32_e32 v175, v175
	v_mul_f32_e32 v192, v79, v192
	v_mul_f32_e32 v193, v75, v193
	v_mul_f32_e32 v174, v71, v174
	v_mul_f32_e32 v175, v67, v175
	v_cvt_pk_bf16_f32 v176, v192, v193
	v_cvt_pk_bf16_f32 v177, v174, v175
	ds_write_b16 v170, v176 offset:7056
	ds_write_b16_d16_hi v170, v176 offset:7088
	ds_write_b16 v170, v177 offset:7120
	ds_write_b16_d16_hi v170, v177 offset:7152
	v_mul_f32_e32 v178, 0xbfb8aa3b, v80
	v_mul_f32_e32 v179, 0xbfb8aa3b, v76
	v_mul_f32_e32 v180, 0xbfb8aa3b, v72
	v_mul_f32_e32 v181, 0xbfb8aa3b, v68
	v_exp_f32_e32 v178, v178
	v_exp_f32_e32 v179, v179
	v_exp_f32_e32 v180, v180
	v_exp_f32_e32 v181, v181
	v_add_f32_e32 v178, 1.0, v178
	v_add_f32_e32 v179, 1.0, v179
	v_add_f32_e32 v180, 1.0, v180
	v_add_f32_e32 v181, 1.0, v181
	v_rcp_f32_e32 v178, v178
	v_rcp_f32_e32 v179, v179
	v_rcp_f32_e32 v180, v180
	v_rcp_f32_e32 v181, v181
	v_mul_f32_e32 v178, v80, v178
	v_mul_f32_e32 v179, v76, v179
	v_mul_f32_e32 v180, v72, v180
	v_mul_f32_e32 v181, v68, v181
	v_cvt_pk_bf16_f32 v182, v178, v179
	v_cvt_pk_bf16_f32 v183, v180, v181
	ds_write_b16 v170, v182 offset:7200
	ds_write_b16_d16_hi v170, v182 offset:7232
	ds_write_b16 v170, v183 offset:7264
	ds_write_b16_d16_hi v170, v183 offset:7296
	v_mul_f32_e32 v184, 0xbfb8aa3b, v81
	v_mul_f32_e32 v185, 0xbfb8aa3b, v77
	v_mul_f32_e32 v186, 0xbfb8aa3b, v73
	v_mul_f32_e32 v187, 0xbfb8aa3b, v69
	v_exp_f32_e32 v184, v184
	v_exp_f32_e32 v185, v185
	v_exp_f32_e32 v186, v186
	v_exp_f32_e32 v187, v187
	v_add_f32_e32 v184, 1.0, v184
	v_add_f32_e32 v185, 1.0, v185
	v_add_f32_e32 v186, 1.0, v186
	v_add_f32_e32 v187, 1.0, v187
	v_rcp_f32_e32 v184, v184
	v_rcp_f32_e32 v185, v185
	v_rcp_f32_e32 v186, v186
	v_rcp_f32_e32 v187, v187
	v_mul_f32_e32 v184, v81, v184
	v_mul_f32_e32 v185, v77, v185
	v_mul_f32_e32 v186, v73, v186
	v_mul_f32_e32 v187, v69, v187
	v_cvt_pk_bf16_f32 v188, v184, v185
	v_cvt_pk_bf16_f32 v189, v186, v187
	ds_write_b16 v170, v188 offset:7344
	ds_write_b16_d16_hi v170, v188 offset:7376
	ds_write_b16 v170, v189 offset:7408
	ds_write_b16_d16_hi v170, v189 offset:7440
	ds_read_b128 v[130:133], v171 offset:0
	ds_read_b128 v[134:137], v171 offset:1152
	ds_read_b128 v[138:141], v171 offset:2304
	ds_read_b128 v[142:145], v171 offset:3456
	ds_read_b128 v[146:149], v171 offset:4608
	ds_read_b128 v[150:153], v171 offset:5760
	ds_read_b128 v[154:157], v171 offset:6912
	ds_read_b128 v[158:161], v171 offset:8064
	s_waitcnt lgkmcnt(7)
	global_store_dwordx4 v172, v[130:133], s[44:45] offset:0
	s_waitcnt lgkmcnt(6)
	global_store_dwordx4 v172, v[134:137], s[44:45] offset:1024
	s_waitcnt lgkmcnt(5)
	global_store_dwordx4 v172, v[138:141], s[44:45] offset:2048
	s_waitcnt lgkmcnt(4)
	global_store_dwordx4 v172, v[142:145], s[44:45] offset:3072
	s_waitcnt lgkmcnt(3)
	global_store_dwordx4 v172, v[146:149], s[62:63] offset:0
	s_waitcnt lgkmcnt(2)
	global_store_dwordx4 v172, v[150:153], s[62:63] offset:1024
	s_waitcnt lgkmcnt(1)
	global_store_dwordx4 v172, v[154:157], s[62:63] offset:2048
	s_waitcnt lgkmcnt(0)
; DI float silu(float v) { return v * __builtin_amdgcn_rcpf(1.f + __builtin_amdgcn_exp2f(-1.4426950408889634f * v)); }
; template <int EPI>
; DI void gemm_phase(const P& p, int l, const u16* __restrict__ A, const u16* __restrict__ Bt, int mpx, char* lds) {
;     ...
;     for (int hf = 0; hf < 2; ++hf) {
; #pragma unroll
;       for (int mi = 0; mi < 4; ++mi) {
; #pragma unroll
;         for (int j = 0; j < 4; ++j) {
;           float v0 = acc[hf * 4 + mi][0][j], v1 = acc[hf * 4 + mi][1][j], v2 = acc[hf * 4 + mi][2][j], v3 = acc[hf * 4 + mi][3][j];
;           const int rowl = mi * 16 + g * 4 + j;
;           const int s = tokw + hf * 64 + rowl;
;           if (tr == 1) {
;             v0 = silu(v0); v1 = silu(v1); v2 = silu(v2); v3 = silu(v3);
;     ...
;           const unsigned u01 = pack2(v0, v1), u23 = pack2(v2, v3);
;           if (kind == 1) {
;             Tl[(0 * 16 + r) * 72 + rowl] = (u16)u01;
;             Tl[(1 * 16 + r) * 72 + rowl] = (u16)(u01 >> 16);
;             Tl[(2 * 16 + r) * 72 + rowl] = (u16)u23;
;             Tl[(3 * 16 + r) * 72 + rowl] = (u16)(u23 >> 16);
;           } else if (tr == 2) {
;             Tl[rowl * 72 + 0 * 16 + r] = f2h(v0);
;             Tl[rowl * 72 + 1 * 16 + r] = f2h(v1);
;             Tl[rowl * 72 + 2 * 16 + r] = f2h(v2);
;             Tl[rowl * 72 + 3 * 16 + r] = f2h(v3);
;           } else {
;             Tl[rowl * 72 + 0 * 16 + r] = (u16)u01;
;             Tl[rowl * 72 + 1 * 16 + r] = (u16)(u01 >> 16);
;             Tl[rowl * 72 + 2 * 16 + r] = (u16)u23;
;             Tl[rowl * 72 + 3 * 16 + r] = (u16)(u23 >> 16);
;           }
	global_store_dwordx4 v172, v[158:161], s[62:63] offset:3072
	s_add_u32 s44, s44, 0x2000
	s_addc_u32 s45, s45, 0
	s_add_u32 s62, s62, 0x2000
	s_addc_u32 s63, s63, 0
	v_mul_f32_e32 v174, 0xbfb8aa3b, v62
	v_mul_f32_e32 v175, 0xbfb8aa3b, v58
	v_mul_f32_e32 v176, 0xbfb8aa3b, v54
	v_mul_f32_e32 v177, 0xbfb8aa3b, v50
	v_exp_f32_e32 v174, v174
	v_exp_f32_e32 v175, v175
	v_exp_f32_e32 v176, v176
	v_exp_f32_e32 v177, v177
	v_add_f32_e32 v174, 1.0, v174
	v_add_f32_e32 v175, 1.0, v175
	v_add_f32_e32 v176, 1.0, v176
	v_add_f32_e32 v177, 1.0, v177
	v_rcp_f32_e32 v174, v174
	v_rcp_f32_e32 v175, v175
	v_rcp_f32_e32 v176, v176
	v_rcp_f32_e32 v177, v177
	v_mul_f32_e32 v174, v62, v174
	v_mul_f32_e32 v175, v58, v175
	v_mul_f32_e32 v176, v54, v176
	v_mul_f32_e32 v177, v50, v177
	v_cvt_pk_bf16_f32 v178, v174, v175
	v_cvt_pk_bf16_f32 v179, v176, v177
	ds_write_b16 v170, v178 offset:0
	ds_write_b16_d16_hi v170, v178 offset:32
	ds_write_b16 v170, v179 offset:64
	ds_write_b16_d16_hi v170, v179 offset:96
	v_mul_f32_e32 v180, 0xbfb8aa3b, v63
	v_mul_f32_e32 v181, 0xbfb8aa3b, v59
	v_mul_f32_e32 v182, 0xbfb8aa3b, v55
	v_mul_f32_e32 v183, 0xbfb8aa3b, v51
	v_exp_f32_e32 v180, v180
	v_exp_f32_e32 v181, v181
	v_exp_f32_e32 v182, v182
	v_exp_f32_e32 v183, v183
	v_add_f32_e32 v180, 1.0, v180
	v_add_f32_e32 v181, 1.0, v181
	v_add_f32_e32 v182, 1.0, v182
	v_add_f32_e32 v183, 1.0, v183
	v_rcp_f32_e32 v180, v180
	v_rcp_f32_e32 v181, v181
	v_rcp_f32_e32 v182, v182
	v_rcp_f32_e32 v183, v183
	v_mul_f32_e32 v180, v63, v180
	v_mul_f32_e32 v181, v59, v181
	v_mul_f32_e32 v182, v55, v182
	v_mul_f32_e32 v183, v51, v183
	v_cvt_pk_bf16_f32 v184, v180, v181
	v_cvt_pk_bf16_f32 v185, v182, v183
	ds_write_b16 v170, v184 offset:144
	ds_write_b16_d16_hi v170, v184 offset:176
	ds_write_b16 v170, v185 offset:208
	ds_write_b16_d16_hi v170, v185 offset:240
	v_mul_f32_e32 v186, 0xbfb8aa3b, v64
	v_mul_f32_e32 v187, 0xbfb8aa3b, v60
	v_mul_f32_e32 v188, 0xbfb8aa3b, v56
	v_mul_f32_e32 v189, 0xbfb8aa3b, v52
	v_exp_f32_e32 v186, v186
	v_exp_f32_e32 v187, v187
	v_exp_f32_e32 v188, v188
	v_exp_f32_e32 v189, v189
	v_add_f32_e32 v186, 1.0, v186
	v_add_f32_e32 v187, 1.0, v187
	v_add_f32_e32 v188, 1.0, v188
	v_add_f32_e32 v189, 1.0, v189
	v_rcp_f32_e32 v186, v186
	v_rcp_f32_e32 v187, v187
	v_rcp_f32_e32 v188, v188
	v_rcp_f32_e32 v189, v189
	v_mul_f32_e32 v186, v64, v186
	v_mul_f32_e32 v187, v60, v187
	v_mul_f32_e32 v188, v56, v188
	v_mul_f32_e32 v189, v52, v189
	v_cvt_pk_bf16_f32 v190, v186, v187
	v_cvt_pk_bf16_f32 v191, v188, v189
	ds_write_b16 v170, v190 offset:288
	ds_write_b16_d16_hi v170, v190 offset:320
	ds_write_b16 v170, v191 offset:352
	ds_write_b16_d16_hi v170, v191 offset:384
	v_mul_f32_e32 v192, 0xbfb8aa3b, v65
	v_mul_f32_e32 v193, 0xbfb8aa3b, v61
	v_mul_f32_e32 v174, 0xbfb8aa3b, v57
	v_mul_f32_e32 v175, 0xbfb8aa3b, v53
	v_exp_f32_e32 v192, v192
	v_exp_f32_e32 v193, v193
	v_exp_f32_e32 v174, v174
	v_exp_f32_e32 v175, v175
	v_add_f32_e32 v192, 1.0, v192
	v_add_f32_e32 v193, 1.0, v193
	v_add_f32_e32 v174, 1.0, v174
	v_add_f32_e32 v175, 1.0, v175
	v_rcp_f32_e32 v192, v192
	v_rcp_f32_e32 v193, v193
	v_rcp_f32_e32 v174, v174
	v_rcp_f32_e32 v175, v175
	v_mul_f32_e32 v192, v65, v192
	v_mul_f32_e32 v193, v61, v193
	v_mul_f32_e32 v174, v57, v174
	v_mul_f32_e32 v175, v53, v175
	v_cvt_pk_bf16_f32 v176, v192, v193
	v_cvt_pk_bf16_f32 v177, v174, v175
	ds_write_b16 v170, v176 offset:432
	ds_write_b16_d16_hi v170, v176 offset:464
	ds_write_b16 v170, v177 offset:496
	ds_write_b16_d16_hi v170, v177 offset:528
	v_mul_f32_e32 v178, 0xbfb8aa3b, v46
	v_mul_f32_e32 v179, 0xbfb8aa3b, v42
	v_mul_f32_e32 v180, 0xbfb8aa3b, v38
	v_mul_f32_e32 v181, 0xbfb8aa3b, v34
	v_exp_f32_e32 v178, v178
	v_exp_f32_e32 v179, v179
	v_exp_f32_e32 v180, v180
	v_exp_f32_e32 v181, v181
	v_add_f32_e32 v178, 1.0, v178
	v_add_f32_e32 v179, 1.0, v179
	v_add_f32_e32 v180, 1.0, v180
	v_add_f32_e32 v181, 1.0, v181
	v_rcp_f32_e32 v178, v178
	v_rcp_f32_e32 v179, v179
	v_rcp_f32_e32 v180, v180
	v_rcp_f32_e32 v181, v181
	v_mul_f32_e32 v178, v46, v178
	v_mul_f32_e32 v179, v42, v179
	v_mul_f32_e32 v180, v38, v180
	v_mul_f32_e32 v181, v34, v181
	v_cvt_pk_bf16_f32 v182, v178, v179
	v_cvt_pk_bf16_f32 v183, v180, v181
	ds_write_b16 v170, v182 offset:2304
	ds_write_b16_d16_hi v170, v182 offset:2336
	ds_write_b16 v170, v183 offset:2368
	ds_write_b16_d16_hi v170, v183 offset:2400
	v_mul_f32_e32 v184, 0xbfb8aa3b, v47
	v_mul_f32_e32 v185, 0xbfb8aa3b, v43
	v_mul_f32_e32 v186, 0xbfb8aa3b, v39
	v_mul_f32_e32 v187, 0xbfb8aa3b, v35
	v_exp_f32_e32 v184, v184
	v_exp_f32_e32 v185, v185
	v_exp_f32_e32 v186, v186
	v_exp_f32_e32 v187, v187
	v_add_f32_e32 v184, 1.0, v184
	v_add_f32_e32 v185, 1.0, v185
	v_add_f32_e32 v186, 1.0, v186
	v_add_f32_e32 v187, 1.0, v187
	v_rcp_f32_e32 v184, v184
	v_rcp_f32_e32 v185, v185
	v_rcp_f32_e32 v186, v186
	v_rcp_f32_e32 v187, v187
	v_mul_f32_e32 v184, v47, v184
	v_mul_f32_e32 v185, v43, v185
	v_mul_f32_e32 v186, v39, v186
	v_mul_f32_e32 v187, v35, v187
	v_cvt_pk_bf16_f32 v188, v184, v185
	v_cvt_pk_bf16_f32 v189, v186, v187
	ds_write_b16 v170, v188 offset:2448
	ds_write_b16_d16_hi v170, v188 offset:2480
	ds_write_b16 v170, v189 offset:2512
	ds_write_b16_d16_hi v170, v189 offset:2544
	v_mul_f32_e32 v190, 0xbfb8aa3b, v48
	v_mul_f32_e32 v191, 0xbfb8aa3b, v44
	v_mul_f32_e32 v192, 0xbfb8aa3b, v40
	v_mul_f32_e32 v193, 0xbfb8aa3b, v36
	v_exp_f32_e32 v190, v190
	v_exp_f32_e32 v191, v191
	v_exp_f32_e32 v192, v192
	v_exp_f32_e32 v193, v193
	v_add_f32_e32 v190, 1.0, v190
	v_add_f32_e32 v191, 1.0, v191
	v_add_f32_e32 v192, 1.0, v192
	v_add_f32_e32 v193, 1.0, v193
	v_rcp_f32_e32 v190, v190
	v_rcp_f32_e32 v191, v191
	v_rcp_f32_e32 v192, v192
	v_rcp_f32_e32 v193, v193
; DI float silu(float v) { return v * __builtin_amdgcn_rcpf(1.f + __builtin_amdgcn_exp2f(-1.4426950408889634f * v)); }
; template <int EPI>
; DI void gemm_phase(const P& p, int l, const u16* __restrict__ A, const u16* __restrict__ Bt, int mpx, char* lds) {
;     ...
;         for (int j = 0; j < 4; ++j) {
;           float v0 = acc[hf * 4 + mi][0][j], v1 = acc[hf * 4 + mi][1][j], v2 = acc[hf * 4 + mi][2][j], v3 = acc[hf * 4 + mi][3][j];
;           const int rowl = mi * 16 + g * 4 + j;
;           const int s = tokw + hf * 64 + rowl;
;           if (tr == 1) {
;             v0 = silu(v0); v1 = silu(v1); v2 = silu(v2); v3 = silu(v3);
;     ...
;           const unsigned u01 = pack2(v0, v1), u23 = pack2(v2, v3);
;           if (kind == 1) {
;             Tl[(0 * 16 + r) * 72 + rowl] = (u16)u01;
;             Tl[(1 * 16 + r) * 72 + rowl] = (u16)(u01 >> 16);
;             Tl[(2 * 16 + r) * 72 + rowl] = (u16)u23;
;             Tl[(3 * 16 + r) * 72 + rowl] = (u16)(u23 >> 16);
;           } else if (tr == 2) {
;             Tl[rowl * 72 + 0 * 16 + r] = f2h(v0);
;             Tl[rowl * 72 + 1 * 16 + r] = f2h(v1);
;             Tl[rowl * 72 + 2 * 16 + r] = f2h(v2);
;             Tl[rowl * 72 + 3 * 16 + r] = f2h(v3);
;           } else {
;             Tl[rowl * 72 + 0 * 16 + r] = (u16)u01;
;             Tl[rowl * 72 + 1 * 16 + r] = (u16)(u01 >> 16);
;             Tl[rowl * 72 + 2 * 16 + r] = (u16)u23;
;             Tl[rowl * 72 + 3 * 16 + r] = (u16)(u23 >> 16);
;           }
	v_mul_f32_e32 v190, v48, v190
	v_mul_f32_e32 v191, v44, v191
	v_mul_f32_e32 v192, v40, v192
	v_mul_f32_e32 v193, v36, v193
	v_cvt_pk_bf16_f32 v174, v190, v191
	v_cvt_pk_bf16_f32 v175, v192, v193
	ds_write_b16 v170, v174 offset:2592
	ds_write_b16_d16_hi v170, v174 offset:2624
	ds_write_b16 v170, v175 offset:2656
	ds_write_b16_d16_hi v170, v175 offset:2688
	v_mul_f32_e32 v176, 0xbfb8aa3b, v49
	v_mul_f32_e32 v177, 0xbfb8aa3b, v45
	v_mul_f32_e32 v178, 0xbfb8aa3b, v41
	v_mul_f32_e32 v179, 0xbfb8aa3b, v37
	v_exp_f32_e32 v176, v176
	v_exp_f32_e32 v177, v177
	v_exp_f32_e32 v178, v178
	v_exp_f32_e32 v179, v179
	v_add_f32_e32 v176, 1.0, v176
	v_add_f32_e32 v177, 1.0, v177
	v_add_f32_e32 v178, 1.0, v178
	v_add_f32_e32 v179, 1.0, v179
	v_rcp_f32_e32 v176, v176
	v_rcp_f32_e32 v177, v177
	v_rcp_f32_e32 v178, v178
	v_rcp_f32_e32 v179, v179
	v_mul_f32_e32 v176, v49, v176
	v_mul_f32_e32 v177, v45, v177
	v_mul_f32_e32 v178, v41, v178
	v_mul_f32_e32 v179, v37, v179
	v_cvt_pk_bf16_f32 v180, v176, v177
	v_cvt_pk_bf16_f32 v181, v178, v179
	ds_write_b16 v170, v180 offset:2736
	ds_write_b16_d16_hi v170, v180 offset:2768
	ds_write_b16 v170, v181 offset:2800
	ds_write_b16_d16_hi v170, v181 offset:2832
	v_mul_f32_e32 v182, 0xbfb8aa3b, v30
	v_mul_f32_e32 v183, 0xbfb8aa3b, v26
	v_mul_f32_e32 v184, 0xbfb8aa3b, v22
	v_mul_f32_e32 v185, 0xbfb8aa3b, v18
	v_exp_f32_e32 v182, v182
	v_exp_f32_e32 v183, v183
	v_exp_f32_e32 v184, v184
	v_exp_f32_e32 v185, v185
	v_add_f32_e32 v182, 1.0, v182
	v_add_f32_e32 v183, 1.0, v183
	v_add_f32_e32 v184, 1.0, v184
	v_add_f32_e32 v185, 1.0, v185
	v_rcp_f32_e32 v182, v182
	v_rcp_f32_e32 v183, v183
	v_rcp_f32_e32 v184, v184
	v_rcp_f32_e32 v185, v185
	v_mul_f32_e32 v182, v30, v182
	v_mul_f32_e32 v183, v26, v183
	v_mul_f32_e32 v184, v22, v184
	v_mul_f32_e32 v185, v18, v185
	v_cvt_pk_bf16_f32 v186, v182, v183
	v_cvt_pk_bf16_f32 v187, v184, v185
	ds_write_b16 v170, v186 offset:4608
	ds_write_b16_d16_hi v170, v186 offset:4640
	ds_write_b16 v170, v187 offset:4672
	ds_write_b16_d16_hi v170, v187 offset:4704
	v_mul_f32_e32 v188, 0xbfb8aa3b, v31
	v_mul_f32_e32 v189, 0xbfb8aa3b, v27
	v_mul_f32_e32 v190, 0xbfb8aa3b, v23
	v_mul_f32_e32 v191, 0xbfb8aa3b, v19
	v_exp_f32_e32 v188, v188
	v_exp_f32_e32 v189, v189
	v_exp_f32_e32 v190, v190
	v_exp_f32_e32 v191, v191
	v_add_f32_e32 v188, 1.0, v188
	v_add_f32_e32 v189, 1.0, v189
	v_add_f32_e32 v190, 1.0, v190
	v_add_f32_e32 v191, 1.0, v191
	v_rcp_f32_e32 v188, v188
	v_rcp_f32_e32 v189, v189
	v_rcp_f32_e32 v190, v190
	v_rcp_f32_e32 v191, v191
	v_mul_f32_e32 v188, v31, v188
	v_mul_f32_e32 v189, v27, v189
	v_mul_f32_e32 v190, v23, v190
	v_mul_f32_e32 v191, v19, v191
	v_cvt_pk_bf16_f32 v192, v188, v189
	v_cvt_pk_bf16_f32 v193, v190, v191
	ds_write_b16 v170, v192 offset:4752
	ds_write_b16_d16_hi v170, v192 offset:4784
	ds_write_b16 v170, v193 offset:4816
	ds_write_b16_d16_hi v170, v193 offset:4848
	v_mul_f32_e32 v174, 0xbfb8aa3b, v32
	v_mul_f32_e32 v175, 0xbfb8aa3b, v28
	v_mul_f32_e32 v176, 0xbfb8aa3b, v24
	v_mul_f32_e32 v177, 0xbfb8aa3b, v20
	v_exp_f32_e32 v174, v174
	v_exp_f32_e32 v175, v175
	v_exp_f32_e32 v176, v176
	v_exp_f32_e32 v177, v177
	v_add_f32_e32 v174, 1.0, v174
	v_add_f32_e32 v175, 1.0, v175
	v_add_f32_e32 v176, 1.0, v176
	v_add_f32_e32 v177, 1.0, v177
	v_rcp_f32_e32 v174, v174
	v_rcp_f32_e32 v175, v175
	v_rcp_f32_e32 v176, v176
	v_rcp_f32_e32 v177, v177
	v_mul_f32_e32 v174, v32, v174
	v_mul_f32_e32 v175, v28, v175
	v_mul_f32_e32 v176, v24, v176
	v_mul_f32_e32 v177, v20, v177
	v_cvt_pk_bf16_f32 v178, v174, v175
	v_cvt_pk_bf16_f32 v179, v176, v177
	ds_write_b16 v170, v178 offset:4896
	ds_write_b16_d16_hi v170, v178 offset:4928
	ds_write_b16 v170, v179 offset:4960
	ds_write_b16_d16_hi v170, v179 offset:4992
	v_mul_f32_e32 v180, 0xbfb8aa3b, v33
	v_mul_f32_e32 v181, 0xbfb8aa3b, v29
	v_mul_f32_e32 v182, 0xbfb8aa3b, v25
	v_mul_f32_e32 v183, 0xbfb8aa3b, v21
	v_exp_f32_e32 v180, v180
	v_exp_f32_e32 v181, v181
	v_exp_f32_e32 v182, v182
	v_exp_f32_e32 v183, v183
	v_add_f32_e32 v180, 1.0, v180
	v_add_f32_e32 v181, 1.0, v181
	v_add_f32_e32 v182, 1.0, v182
	v_add_f32_e32 v183, 1.0, v183
	v_rcp_f32_e32 v180, v180
	v_rcp_f32_e32 v181, v181
	v_rcp_f32_e32 v182, v182
	v_rcp_f32_e32 v183, v183
	v_mul_f32_e32 v180, v33, v180
	v_mul_f32_e32 v181, v29, v181
	v_mul_f32_e32 v182, v25, v182
	v_mul_f32_e32 v183, v21, v183
	v_cvt_pk_bf16_f32 v184, v180, v181
	v_cvt_pk_bf16_f32 v185, v182, v183
	ds_write_b16 v170, v184 offset:5040
	ds_write_b16_d16_hi v170, v184 offset:5072
	ds_write_b16 v170, v185 offset:5104
	ds_write_b16_d16_hi v170, v185 offset:5136
	v_mul_f32_e32 v186, 0xbfb8aa3b, v166
	v_mul_f32_e32 v187, 0xbfb8aa3b, v162
	v_mul_f32_e32 v188, 0xbfb8aa3b, v2
	v_mul_f32_e32 v189, 0xbfb8aa3b, v6
	v_exp_f32_e32 v186, v186
	v_exp_f32_e32 v187, v187
	v_exp_f32_e32 v188, v188
	v_exp_f32_e32 v189, v189
	v_add_f32_e32 v186, 1.0, v186
	v_add_f32_e32 v187, 1.0, v187
	v_add_f32_e32 v188, 1.0, v188
	v_add_f32_e32 v189, 1.0, v189
	v_rcp_f32_e32 v186, v186
	v_rcp_f32_e32 v187, v187
	v_rcp_f32_e32 v188, v188
	v_rcp_f32_e32 v189, v189
	v_mul_f32_e32 v186, v166, v186
	v_mul_f32_e32 v187, v162, v187
	v_mul_f32_e32 v188, v2, v188
	v_mul_f32_e32 v189, v6, v189
	v_cvt_pk_bf16_f32 v190, v186, v187
	v_cvt_pk_bf16_f32 v191, v188, v189
	ds_write_b16 v170, v190 offset:6912
	ds_write_b16_d16_hi v170, v190 offset:6944
	ds_write_b16 v170, v191 offset:6976
	ds_write_b16_d16_hi v170, v191 offset:7008
	v_mul_f32_e32 v192, 0xbfb8aa3b, v167
	v_mul_f32_e32 v193, 0xbfb8aa3b, v163
	v_mul_f32_e32 v174, 0xbfb8aa3b, v3
	v_mul_f32_e32 v175, 0xbfb8aa3b, v7
	v_exp_f32_e32 v192, v192
	v_exp_f32_e32 v193, v193
	v_exp_f32_e32 v174, v174
	v_exp_f32_e32 v175, v175
; DI float silu(float v) { return v * __builtin_amdgcn_rcpf(1.f + __builtin_amdgcn_exp2f(-1.4426950408889634f * v)); }
; template <int EPI>
; DI void gemm_phase(const P& p, int l, const u16* __restrict__ A, const u16* __restrict__ Bt, int mpx, char* lds) {
;     ...
;         for (int j = 0; j < 4; ++j) {
;           float v0 = acc[hf * 4 + mi][0][j], v1 = acc[hf * 4 + mi][1][j], v2 = acc[hf * 4 + mi][2][j], v3 = acc[hf * 4 + mi][3][j];
;           const int rowl = mi * 16 + g * 4 + j;
;           const int s = tokw + hf * 64 + rowl;
;           if (tr == 1) {
;             v0 = silu(v0); v1 = silu(v1); v2 = silu(v2); v3 = silu(v3);
;     ...
;           const unsigned u01 = pack2(v0, v1), u23 = pack2(v2, v3);
;           if (kind == 1) {
;             Tl[(0 * 16 + r) * 72 + rowl] = (u16)u01;
;             Tl[(1 * 16 + r) * 72 + rowl] = (u16)(u01 >> 16);
;             Tl[(2 * 16 + r) * 72 + rowl] = (u16)u23;
;             Tl[(3 * 16 + r) * 72 + rowl] = (u16)(u23 >> 16);
;           } else if (tr == 2) {
;             Tl[rowl * 72 + 0 * 16 + r] = f2h(v0);
;             Tl[rowl * 72 + 1 * 16 + r] = f2h(v1);
;             Tl[rowl * 72 + 2 * 16 + r] = f2h(v2);
;             Tl[rowl * 72 + 3 * 16 + r] = f2h(v3);
;           } else {
;             Tl[rowl * 72 + 0 * 16 + r] = (u16)u01;
;             Tl[rowl * 72 + 1 * 16 + r] = (u16)(u01 >> 16);
;             Tl[rowl * 72 + 2 * 16 + r] = (u16)u23;
;             Tl[rowl * 72 + 3 * 16 + r] = (u16)(u23 >> 16);
;           }
;         }
;       }
;       __builtin_amdgcn_fence(__ATOMIC_RELEASE, "wavefront");
;       u16* dh = (kind == 1) ? dst + hf * 64 : dst + (size_t)(hf * 64) * rstride;
; #pragma unroll
;       for (int i = 0; i < 8; ++i) {
;         const int c = lane + i * 64;
;         const int row = c >> 3, cc = c & 7;
;         uint4 v = *(const uint4*)&Tl[row * 72 + cc * 8];
;         *(uint4*)(dh + (size_t)row * rstride + cc * 8) = v;
;       }
	v_add_f32_e32 v192, 1.0, v192
	v_add_f32_e32 v193, 1.0, v193
	v_add_f32_e32 v174, 1.0, v174
	v_add_f32_e32 v175, 1.0, v175
	v_rcp_f32_e32 v192, v192
	v_rcp_f32_e32 v193, v193
	v_rcp_f32_e32 v174, v174
	v_rcp_f32_e32 v175, v175
	v_mul_f32_e32 v192, v167, v192
	v_mul_f32_e32 v193, v163, v193
	v_mul_f32_e32 v174, v3, v174
	v_mul_f32_e32 v175, v7, v175
	v_cvt_pk_bf16_f32 v176, v192, v193
	v_cvt_pk_bf16_f32 v177, v174, v175
	ds_write_b16 v170, v176 offset:7056
	ds_write_b16_d16_hi v170, v176 offset:7088
	ds_write_b16 v170, v177 offset:7120
	ds_write_b16_d16_hi v170, v177 offset:7152
	v_mul_f32_e32 v178, 0xbfb8aa3b, v168
	v_mul_f32_e32 v179, 0xbfb8aa3b, v164
	v_mul_f32_e32 v180, 0xbfb8aa3b, v4
	v_mul_f32_e32 v181, 0xbfb8aa3b, v8
	v_exp_f32_e32 v178, v178
	v_exp_f32_e32 v179, v179
	v_exp_f32_e32 v180, v180
	v_exp_f32_e32 v181, v181
	v_add_f32_e32 v178, 1.0, v178
	v_add_f32_e32 v179, 1.0, v179
	v_add_f32_e32 v180, 1.0, v180
	v_add_f32_e32 v181, 1.0, v181
	v_rcp_f32_e32 v178, v178
	v_rcp_f32_e32 v179, v179
	v_rcp_f32_e32 v180, v180
	v_rcp_f32_e32 v181, v181
	v_mul_f32_e32 v178, v168, v178
	v_mul_f32_e32 v179, v164, v179
	v_mul_f32_e32 v180, v4, v180
	v_mul_f32_e32 v181, v8, v181
	v_cvt_pk_bf16_f32 v182, v178, v179
	v_cvt_pk_bf16_f32 v183, v180, v181
	ds_write_b16 v170, v182 offset:7200
	ds_write_b16_d16_hi v170, v182 offset:7232
	ds_write_b16 v170, v183 offset:7264
	ds_write_b16_d16_hi v170, v183 offset:7296
	v_mul_f32_e32 v184, 0xbfb8aa3b, v169
	v_mul_f32_e32 v185, 0xbfb8aa3b, v165
	v_mul_f32_e32 v186, 0xbfb8aa3b, v5
	v_mul_f32_e32 v187, 0xbfb8aa3b, v9
	v_exp_f32_e32 v184, v184
	v_exp_f32_e32 v185, v185
	v_exp_f32_e32 v186, v186
	v_exp_f32_e32 v187, v187
	v_add_f32_e32 v184, 1.0, v184
	v_add_f32_e32 v185, 1.0, v185
	v_add_f32_e32 v186, 1.0, v186
	v_add_f32_e32 v187, 1.0, v187
	v_rcp_f32_e32 v184, v184
	v_rcp_f32_e32 v185, v185
	v_rcp_f32_e32 v186, v186
	v_rcp_f32_e32 v187, v187
	v_mul_f32_e32 v184, v169, v184
	v_mul_f32_e32 v185, v165, v185
	v_mul_f32_e32 v186, v5, v186
	v_mul_f32_e32 v187, v9, v187
	v_cvt_pk_bf16_f32 v188, v184, v185
	v_cvt_pk_bf16_f32 v189, v186, v187
	ds_write_b16 v170, v188 offset:7344
	ds_write_b16_d16_hi v170, v188 offset:7376
	ds_write_b16 v170, v189 offset:7408
	ds_write_b16_d16_hi v170, v189 offset:7440
	ds_read_b128 v[130:133], v171 offset:0
	ds_read_b128 v[134:137], v171 offset:1152
	ds_read_b128 v[138:141], v171 offset:2304
	ds_read_b128 v[142:145], v171 offset:3456
	ds_read_b128 v[146:149], v171 offset:4608
	ds_read_b128 v[150:153], v171 offset:5760
	ds_read_b128 v[154:157], v171 offset:6912
	ds_read_b128 v[158:161], v171 offset:8064
	s_waitcnt lgkmcnt(7)
	global_store_dwordx4 v172, v[130:133], s[44:45] offset:0
	s_waitcnt lgkmcnt(6)
	global_store_dwordx4 v172, v[134:137], s[44:45] offset:1024
	s_waitcnt lgkmcnt(5)
	global_store_dwordx4 v172, v[138:141], s[44:45] offset:2048
	s_waitcnt lgkmcnt(4)
	global_store_dwordx4 v172, v[142:145], s[44:45] offset:3072
	s_waitcnt lgkmcnt(3)
	global_store_dwordx4 v172, v[146:149], s[62:63] offset:0
	s_waitcnt lgkmcnt(2)
	global_store_dwordx4 v172, v[150:153], s[62:63] offset:1024
	s_waitcnt lgkmcnt(1)
	global_store_dwordx4 v172, v[154:157], s[62:63] offset:2048
	s_waitcnt lgkmcnt(0)
	global_store_dwordx4 v172, v[158:161], s[62:63] offset:3072
	s_branch .Lfe_done
.Lfe_k0_plain:
	s_add_u32 s62, s44, 0x1000
	s_addc_u32 s63, s45, 0
	v_cvt_pk_bf16_f32 v178, v126, v122
	v_cvt_pk_bf16_f32 v179, v118, v114
	ds_write_b16 v170, v178 offset:0
	ds_write_b16_d16_hi v170, v178 offset:32
	ds_write_b16 v170, v179 offset:64
	ds_write_b16_d16_hi v170, v179 offset:96
	v_cvt_pk_bf16_f32 v184, v127, v123
	v_cvt_pk_bf16_f32 v185, v119, v115
	ds_write_b16 v170, v184 offset:144
	ds_write_b16_d16_hi v170, v184 offset:176
	ds_write_b16 v170, v185 offset:208
	ds_write_b16_d16_hi v170, v185 offset:240
	v_cvt_pk_bf16_f32 v190, v128, v124
	v_cvt_pk_bf16_f32 v191, v120, v116
	ds_write_b16 v170, v190 offset:288
	ds_write_b16_d16_hi v170, v190 offset:320
	ds_write_b16 v170, v191 offset:352
	ds_write_b16_d16_hi v170, v191 offset:384
	v_cvt_pk_bf16_f32 v176, v129, v125
	v_cvt_pk_bf16_f32 v177, v121, v117
	ds_write_b16 v170, v176 offset:432
	ds_write_b16_d16_hi v170, v176 offset:464
	ds_write_b16 v170, v177 offset:496
	ds_write_b16_d16_hi v170, v177 offset:528
	v_cvt_pk_bf16_f32 v182, v110, v106
	v_cvt_pk_bf16_f32 v183, v102, v98
	ds_write_b16 v170, v182 offset:2304
	ds_write_b16_d16_hi v170, v182 offset:2336
	ds_write_b16 v170, v183 offset:2368
	ds_write_b16_d16_hi v170, v183 offset:2400
	v_cvt_pk_bf16_f32 v188, v111, v107
	v_cvt_pk_bf16_f32 v189, v103, v99
	ds_write_b16 v170, v188 offset:2448
	ds_write_b16_d16_hi v170, v188 offset:2480
	ds_write_b16 v170, v189 offset:2512
	ds_write_b16_d16_hi v170, v189 offset:2544
	v_cvt_pk_bf16_f32 v174, v112, v108
	v_cvt_pk_bf16_f32 v175, v104, v100
	ds_write_b16 v170, v174 offset:2592
	ds_write_b16_d16_hi v170, v174 offset:2624
	ds_write_b16 v170, v175 offset:2656
	ds_write_b16_d16_hi v170, v175 offset:2688
	v_cvt_pk_bf16_f32 v180, v113, v109
	v_cvt_pk_bf16_f32 v181, v105, v101
	ds_write_b16 v170, v180 offset:2736
	ds_write_b16_d16_hi v170, v180 offset:2768
	ds_write_b16 v170, v181 offset:2800
	ds_write_b16_d16_hi v170, v181 offset:2832
	v_cvt_pk_bf16_f32 v186, v94, v90
	v_cvt_pk_bf16_f32 v187, v86, v82
	ds_write_b16 v170, v186 offset:4608
	ds_write_b16_d16_hi v170, v186 offset:4640
	ds_write_b16 v170, v187 offset:4672
	ds_write_b16_d16_hi v170, v187 offset:4704
	v_cvt_pk_bf16_f32 v192, v95, v91
	v_cvt_pk_bf16_f32 v193, v87, v83
	ds_write_b16 v170, v192 offset:4752
	ds_write_b16_d16_hi v170, v192 offset:4784
	ds_write_b16 v170, v193 offset:4816
	ds_write_b16_d16_hi v170, v193 offset:4848
; template <int EPI>
; DI void gemm_phase(const P& p, int l, const u16* __restrict__ A, const u16* __restrict__ Bt, int mpx, char* lds) {
;     ...
;           const unsigned u01 = pack2(v0, v1), u23 = pack2(v2, v3);
;           if (kind == 1) {
;             Tl[(0 * 16 + r) * 72 + rowl] = (u16)u01;
;             Tl[(1 * 16 + r) * 72 + rowl] = (u16)(u01 >> 16);
;             Tl[(2 * 16 + r) * 72 + rowl] = (u16)u23;
;             Tl[(3 * 16 + r) * 72 + rowl] = (u16)(u23 >> 16);
;           } else if (tr == 2) {
;             Tl[rowl * 72 + 0 * 16 + r] = f2h(v0);
;             Tl[rowl * 72 + 1 * 16 + r] = f2h(v1);
;             Tl[rowl * 72 + 2 * 16 + r] = f2h(v2);
;             Tl[rowl * 72 + 3 * 16 + r] = f2h(v3);
;           } else {
;             Tl[rowl * 72 + 0 * 16 + r] = (u16)u01;
;             Tl[rowl * 72 + 1 * 16 + r] = (u16)(u01 >> 16);
;             Tl[rowl * 72 + 2 * 16 + r] = (u16)u23;
;             Tl[rowl * 72 + 3 * 16 + r] = (u16)(u23 >> 16);
;           }
;         }
;       }
;       __builtin_amdgcn_fence(__ATOMIC_RELEASE, "wavefront");
;       u16* dh = (kind == 1) ? dst + hf * 64 : dst + (size_t)(hf * 64) * rstride;
; #pragma unroll
;       for (int i = 0; i < 8; ++i) {
;         const int c = lane + i * 64;
;         const int row = c >> 3, cc = c & 7;
;         uint4 v = *(const uint4*)&Tl[row * 72 + cc * 8];
;         *(uint4*)(dh + (size_t)row * rstride + cc * 8) = v;
;       }
	v_cvt_pk_bf16_f32 v178, v96, v92
	v_cvt_pk_bf16_f32 v179, v88, v84
	ds_write_b16 v170, v178 offset:4896
	ds_write_b16_d16_hi v170, v178 offset:4928
	ds_write_b16 v170, v179 offset:4960
	ds_write_b16_d16_hi v170, v179 offset:4992
	v_cvt_pk_bf16_f32 v184, v97, v93
	v_cvt_pk_bf16_f32 v185, v89, v85
	ds_write_b16 v170, v184 offset:5040
	ds_write_b16_d16_hi v170, v184 offset:5072
	ds_write_b16 v170, v185 offset:5104
	ds_write_b16_d16_hi v170, v185 offset:5136
	v_cvt_pk_bf16_f32 v190, v78, v74
	v_cvt_pk_bf16_f32 v191, v70, v66
	ds_write_b16 v170, v190 offset:6912
	ds_write_b16_d16_hi v170, v190 offset:6944
	ds_write_b16 v170, v191 offset:6976
	ds_write_b16_d16_hi v170, v191 offset:7008
	v_cvt_pk_bf16_f32 v176, v79, v75
	v_cvt_pk_bf16_f32 v177, v71, v67
	ds_write_b16 v170, v176 offset:7056
	ds_write_b16_d16_hi v170, v176 offset:7088
	ds_write_b16 v170, v177 offset:7120
	ds_write_b16_d16_hi v170, v177 offset:7152
	v_cvt_pk_bf16_f32 v182, v80, v76
	v_cvt_pk_bf16_f32 v183, v72, v68
	ds_write_b16 v170, v182 offset:7200
	ds_write_b16_d16_hi v170, v182 offset:7232
	ds_write_b16 v170, v183 offset:7264
	ds_write_b16_d16_hi v170, v183 offset:7296
	v_cvt_pk_bf16_f32 v188, v81, v77
	v_cvt_pk_bf16_f32 v189, v73, v69
	ds_write_b16 v170, v188 offset:7344
	ds_write_b16_d16_hi v170, v188 offset:7376
	ds_write_b16 v170, v189 offset:7408
	ds_write_b16_d16_hi v170, v189 offset:7440
	ds_read_b128 v[130:133], v171 offset:0
	ds_read_b128 v[134:137], v171 offset:1152
	ds_read_b128 v[138:141], v171 offset:2304
	ds_read_b128 v[142:145], v171 offset:3456
	ds_read_b128 v[146:149], v171 offset:4608
	ds_read_b128 v[150:153], v171 offset:5760
	ds_read_b128 v[154:157], v171 offset:6912
	ds_read_b128 v[158:161], v171 offset:8064
	s_waitcnt lgkmcnt(7)
	global_store_dwordx4 v172, v[130:133], s[44:45] offset:0
	s_waitcnt lgkmcnt(6)
	global_store_dwordx4 v172, v[134:137], s[44:45] offset:1024
	s_waitcnt lgkmcnt(5)
	global_store_dwordx4 v172, v[138:141], s[44:45] offset:2048
	s_waitcnt lgkmcnt(4)
	global_store_dwordx4 v172, v[142:145], s[44:45] offset:3072
	s_waitcnt lgkmcnt(3)
	global_store_dwordx4 v172, v[146:149], s[62:63] offset:0
	s_waitcnt lgkmcnt(2)
	global_store_dwordx4 v172, v[150:153], s[62:63] offset:1024
	s_waitcnt lgkmcnt(1)
	global_store_dwordx4 v172, v[154:157], s[62:63] offset:2048
	s_waitcnt lgkmcnt(0)
	global_store_dwordx4 v172, v[158:161], s[62:63] offset:3072
	s_add_u32 s44, s44, 0x2000
	s_addc_u32 s45, s45, 0
	s_add_u32 s62, s62, 0x2000
	s_addc_u32 s63, s63, 0
	v_cvt_pk_bf16_f32 v178, v62, v58
	v_cvt_pk_bf16_f32 v179, v54, v50
	ds_write_b16 v170, v178 offset:0
	ds_write_b16_d16_hi v170, v178 offset:32
	ds_write_b16 v170, v179 offset:64
	ds_write_b16_d16_hi v170, v179 offset:96
	v_cvt_pk_bf16_f32 v184, v63, v59
	v_cvt_pk_bf16_f32 v185, v55, v51
	ds_write_b16 v170, v184 offset:144
	ds_write_b16_d16_hi v170, v184 offset:176
	ds_write_b16 v170, v185 offset:208
	ds_write_b16_d16_hi v170, v185 offset:240
	v_cvt_pk_bf16_f32 v190, v64, v60
	v_cvt_pk_bf16_f32 v191, v56, v52
	ds_write_b16 v170, v190 offset:288
	ds_write_b16_d16_hi v170, v190 offset:320
	ds_write_b16 v170, v191 offset:352
	ds_write_b16_d16_hi v170, v191 offset:384
	v_cvt_pk_bf16_f32 v176, v65, v61
	v_cvt_pk_bf16_f32 v177, v57, v53
	ds_write_b16 v170, v176 offset:432
	ds_write_b16_d16_hi v170, v176 offset:464
	ds_write_b16 v170, v177 offset:496
	ds_write_b16_d16_hi v170, v177 offset:528
	v_cvt_pk_bf16_f32 v182, v46, v42
	v_cvt_pk_bf16_f32 v183, v38, v34
	ds_write_b16 v170, v182 offset:2304
	ds_write_b16_d16_hi v170, v182 offset:2336
	ds_write_b16 v170, v183 offset:2368
	ds_write_b16_d16_hi v170, v183 offset:2400
	v_cvt_pk_bf16_f32 v188, v47, v43
	v_cvt_pk_bf16_f32 v189, v39, v35
	ds_write_b16 v170, v188 offset:2448
	ds_write_b16_d16_hi v170, v188 offset:2480
	ds_write_b16 v170, v189 offset:2512
	ds_write_b16_d16_hi v170, v189 offset:2544
	v_cvt_pk_bf16_f32 v174, v48, v44
	v_cvt_pk_bf16_f32 v175, v40, v36
	ds_write_b16 v170, v174 offset:2592
	ds_write_b16_d16_hi v170, v174 offset:2624
	ds_write_b16 v170, v175 offset:2656
	ds_write_b16_d16_hi v170, v175 offset:2688
	v_cvt_pk_bf16_f32 v180, v49, v45
	v_cvt_pk_bf16_f32 v181, v41, v37
	ds_write_b16 v170, v180 offset:2736
	ds_write_b16_d16_hi v170, v180 offset:2768
	ds_write_b16 v170, v181 offset:2800
	ds_write_b16_d16_hi v170, v181 offset:2832
	v_cvt_pk_bf16_f32 v186, v30, v26
	v_cvt_pk_bf16_f32 v187, v22, v18
	ds_write_b16 v170, v186 offset:4608
	ds_write_b16_d16_hi v170, v186 offset:4640
	ds_write_b16 v170, v187 offset:4672
	ds_write_b16_d16_hi v170, v187 offset:4704
	v_cvt_pk_bf16_f32 v192, v31, v27
	v_cvt_pk_bf16_f32 v193, v23, v19
	ds_write_b16 v170, v192 offset:4752
	ds_write_b16_d16_hi v170, v192 offset:4784
	ds_write_b16 v170, v193 offset:4816
	ds_write_b16_d16_hi v170, v193 offset:4848
	v_cvt_pk_bf16_f32 v178, v32, v28
	v_cvt_pk_bf16_f32 v179, v24, v20
	ds_write_b16 v170, v178 offset:4896
	ds_write_b16_d16_hi v170, v178 offset:4928
	ds_write_b16 v170, v179 offset:4960
	ds_write_b16_d16_hi v170, v179 offset:4992
	v_cvt_pk_bf16_f32 v184, v33, v29
	v_cvt_pk_bf16_f32 v185, v25, v21
	ds_write_b16 v170, v184 offset:5040
	ds_write_b16_d16_hi v170, v184 offset:5072
	ds_write_b16 v170, v185 offset:5104
	ds_write_b16_d16_hi v170, v185 offset:5136
	v_cvt_pk_bf16_f32 v190, v166, v162
	v_cvt_pk_bf16_f32 v191, v2, v6
	ds_write_b16 v170, v190 offset:6912
	ds_write_b16_d16_hi v170, v190 offset:6944
	ds_write_b16 v170, v191 offset:6976
	ds_write_b16_d16_hi v170, v191 offset:7008
	v_cvt_pk_bf16_f32 v176, v167, v163
	v_cvt_pk_bf16_f32 v177, v3, v7
	ds_write_b16 v170, v176 offset:7056
	ds_write_b16_d16_hi v170, v176 offset:7088
	ds_write_b16 v170, v177 offset:7120
	ds_write_b16_d16_hi v170, v177 offset:7152
	v_cvt_pk_bf16_f32 v182, v168, v164
	v_cvt_pk_bf16_f32 v183, v4, v8
	ds_write_b16 v170, v182 offset:7200
	ds_write_b16_d16_hi v170, v182 offset:7232
	ds_write_b16 v170, v183 offset:7264
	ds_write_b16_d16_hi v170, v183 offset:7296
	v_cvt_pk_bf16_f32 v188, v169, v165
	v_cvt_pk_bf16_f32 v189, v5, v9
	ds_write_b16 v170, v188 offset:7344
	ds_write_b16_d16_hi v170, v188 offset:7376
	ds_write_b16 v170, v189 offset:7408
	ds_write_b16_d16_hi v170, v189 offset:7440
	ds_read_b128 v[130:133], v171 offset:0
	ds_read_b128 v[134:137], v171 offset:1152
	ds_read_b128 v[138:141], v171 offset:2304
	ds_read_b128 v[142:145], v171 offset:3456
	ds_read_b128 v[146:149], v171 offset:4608
	ds_read_b128 v[150:153], v171 offset:5760
	ds_read_b128 v[154:157], v171 offset:6912
	ds_read_b128 v[158:161], v171 offset:8064
	s_waitcnt lgkmcnt(7)
; template <int EPI>
; DI void gemm_phase(const P& p, int l, const u16* __restrict__ A, const u16* __restrict__ Bt, int mpx, char* lds) {
;     ...
;           } else if (tr == 2) {
;             Tl[rowl * 72 + 0 * 16 + r] = f2h(v0);
;             Tl[rowl * 72 + 1 * 16 + r] = f2h(v1);
;             Tl[rowl * 72 + 2 * 16 + r] = f2h(v2);
;             Tl[rowl * 72 + 3 * 16 + r] = f2h(v3);
;           } else {
;             Tl[rowl * 72 + 0 * 16 + r] = (u16)u01;
;             Tl[rowl * 72 + 1 * 16 + r] = (u16)(u01 >> 16);
;             Tl[rowl * 72 + 2 * 16 + r] = (u16)u23;
;             Tl[rowl * 72 + 3 * 16 + r] = (u16)(u23 >> 16);
;           }
;         }
;       }
;       __builtin_amdgcn_fence(__ATOMIC_RELEASE, "wavefront");
;       u16* dh = (kind == 1) ? dst + hf * 64 : dst + (size_t)(hf * 64) * rstride;
; #pragma unroll
;       for (int i = 0; i < 8; ++i) {
;         const int c = lane + i * 64;
;         const int row = c >> 3, cc = c & 7;
;         uint4 v = *(const uint4*)&Tl[row * 72 + cc * 8];
;         *(uint4*)(dh + (size_t)row * rstride + cc * 8) = v;
;       }
	global_store_dwordx4 v172, v[130:133], s[44:45] offset:0
	s_waitcnt lgkmcnt(6)
	global_store_dwordx4 v172, v[134:137], s[44:45] offset:1024
	s_waitcnt lgkmcnt(5)
	global_store_dwordx4 v172, v[138:141], s[44:45] offset:2048
	s_waitcnt lgkmcnt(4)
	global_store_dwordx4 v172, v[142:145], s[44:45] offset:3072
	s_waitcnt lgkmcnt(3)
	global_store_dwordx4 v172, v[146:149], s[62:63] offset:0
	s_waitcnt lgkmcnt(2)
	global_store_dwordx4 v172, v[150:153], s[62:63] offset:1024
	s_waitcnt lgkmcnt(1)
	global_store_dwordx4 v172, v[154:157], s[62:63] offset:2048
	s_waitcnt lgkmcnt(0)
	global_store_dwordx4 v172, v[158:161], s[62:63] offset:3072
	s_branch .Lfe_done
.Lfe_k0_fp16:
	s_add_u32 s62, s44, 0x1000
	s_addc_u32 s63, s45, 0
	v_cvt_f16_f32_e32 v174, v126
	v_cvt_f16_f32_e32 v175, v122
	v_cvt_f16_f32_e32 v176, v118
	v_cvt_f16_f32_e32 v177, v114
	ds_write_b16 v170, v174 offset:0
	ds_write_b16 v170, v175 offset:32
	ds_write_b16 v170, v176 offset:64
	ds_write_b16 v170, v177 offset:96
	v_cvt_f16_f32_e32 v180, v127
	v_cvt_f16_f32_e32 v181, v123
	v_cvt_f16_f32_e32 v182, v119
	v_cvt_f16_f32_e32 v183, v115
	ds_write_b16 v170, v180 offset:144
	ds_write_b16 v170, v181 offset:176
	ds_write_b16 v170, v182 offset:208
	ds_write_b16 v170, v183 offset:240
	v_cvt_f16_f32_e32 v186, v128
	v_cvt_f16_f32_e32 v187, v124
	v_cvt_f16_f32_e32 v188, v120
	v_cvt_f16_f32_e32 v189, v116
	ds_write_b16 v170, v186 offset:288
	ds_write_b16 v170, v187 offset:320
	ds_write_b16 v170, v188 offset:352
	ds_write_b16 v170, v189 offset:384
	v_cvt_f16_f32_e32 v192, v129
	v_cvt_f16_f32_e32 v193, v125
	v_cvt_f16_f32_e32 v174, v121
	v_cvt_f16_f32_e32 v175, v117
	ds_write_b16 v170, v192 offset:432
	ds_write_b16 v170, v193 offset:464
	ds_write_b16 v170, v174 offset:496
	ds_write_b16 v170, v175 offset:528
	v_cvt_f16_f32_e32 v178, v110
	v_cvt_f16_f32_e32 v179, v106
	v_cvt_f16_f32_e32 v180, v102
	v_cvt_f16_f32_e32 v181, v98
	ds_write_b16 v170, v178 offset:2304
	ds_write_b16 v170, v179 offset:2336
	ds_write_b16 v170, v180 offset:2368
	ds_write_b16 v170, v181 offset:2400
	v_cvt_f16_f32_e32 v184, v111
	v_cvt_f16_f32_e32 v185, v107
	v_cvt_f16_f32_e32 v186, v103
	v_cvt_f16_f32_e32 v187, v99
	ds_write_b16 v170, v184 offset:2448
	ds_write_b16 v170, v185 offset:2480
	ds_write_b16 v170, v186 offset:2512
	ds_write_b16 v170, v187 offset:2544
	v_cvt_f16_f32_e32 v190, v112
	v_cvt_f16_f32_e32 v191, v108
	v_cvt_f16_f32_e32 v192, v104
	v_cvt_f16_f32_e32 v193, v100
	ds_write_b16 v170, v190 offset:2592
	ds_write_b16 v170, v191 offset:2624
	ds_write_b16 v170, v192 offset:2656
	ds_write_b16 v170, v193 offset:2688
	v_cvt_f16_f32_e32 v176, v113
	v_cvt_f16_f32_e32 v177, v109
	v_cvt_f16_f32_e32 v178, v105
	v_cvt_f16_f32_e32 v179, v101
	ds_write_b16 v170, v176 offset:2736
	ds_write_b16 v170, v177 offset:2768
	ds_write_b16 v170, v178 offset:2800
	ds_write_b16 v170, v179 offset:2832
	v_cvt_f16_f32_e32 v182, v94
	v_cvt_f16_f32_e32 v183, v90
	v_cvt_f16_f32_e32 v184, v86
	v_cvt_f16_f32_e32 v185, v82
	ds_write_b16 v170, v182 offset:4608
	ds_write_b16 v170, v183 offset:4640
	ds_write_b16 v170, v184 offset:4672
	ds_write_b16 v170, v185 offset:4704
	v_cvt_f16_f32_e32 v188, v95
	v_cvt_f16_f32_e32 v189, v91
	v_cvt_f16_f32_e32 v190, v87
	v_cvt_f16_f32_e32 v191, v83
	ds_write_b16 v170, v188 offset:4752
	ds_write_b16 v170, v189 offset:4784
	ds_write_b16 v170, v190 offset:4816
	ds_write_b16 v170, v191 offset:4848
	v_cvt_f16_f32_e32 v174, v96
	v_cvt_f16_f32_e32 v175, v92
	v_cvt_f16_f32_e32 v176, v88
	v_cvt_f16_f32_e32 v177, v84
	ds_write_b16 v170, v174 offset:4896
	ds_write_b16 v170, v175 offset:4928
	ds_write_b16 v170, v176 offset:4960
	ds_write_b16 v170, v177 offset:4992
	v_cvt_f16_f32_e32 v180, v97
	v_cvt_f16_f32_e32 v181, v93
	v_cvt_f16_f32_e32 v182, v89
	v_cvt_f16_f32_e32 v183, v85
	ds_write_b16 v170, v180 offset:5040
	ds_write_b16 v170, v181 offset:5072
	ds_write_b16 v170, v182 offset:5104
	ds_write_b16 v170, v183 offset:5136
	v_cvt_f16_f32_e32 v186, v78
	v_cvt_f16_f32_e32 v187, v74
	v_cvt_f16_f32_e32 v188, v70
	v_cvt_f16_f32_e32 v189, v66
	ds_write_b16 v170, v186 offset:6912
	ds_write_b16 v170, v187 offset:6944
	ds_write_b16 v170, v188 offset:6976
	ds_write_b16 v170, v189 offset:7008
	v_cvt_f16_f32_e32 v192, v79
	v_cvt_f16_f32_e32 v193, v75
	v_cvt_f16_f32_e32 v174, v71
	v_cvt_f16_f32_e32 v175, v67
	ds_write_b16 v170, v192 offset:7056
	ds_write_b16 v170, v193 offset:7088
	ds_write_b16 v170, v174 offset:7120
	ds_write_b16 v170, v175 offset:7152
	v_cvt_f16_f32_e32 v178, v80
	v_cvt_f16_f32_e32 v179, v76
	v_cvt_f16_f32_e32 v180, v72
	v_cvt_f16_f32_e32 v181, v68
	ds_write_b16 v170, v178 offset:7200
	ds_write_b16 v170, v179 offset:7232
	ds_write_b16 v170, v180 offset:7264
	ds_write_b16 v170, v181 offset:7296
	v_cvt_f16_f32_e32 v184, v81
	v_cvt_f16_f32_e32 v185, v77
	v_cvt_f16_f32_e32 v186, v73
	v_cvt_f16_f32_e32 v187, v69
	ds_write_b16 v170, v184 offset:7344
	ds_write_b16 v170, v185 offset:7376
	ds_write_b16 v170, v186 offset:7408
	ds_write_b16 v170, v187 offset:7440
	ds_read_b128 v[130:133], v171 offset:0
	ds_read_b128 v[134:137], v171 offset:1152
	ds_read_b128 v[138:141], v171 offset:2304
	ds_read_b128 v[142:145], v171 offset:3456
	ds_read_b128 v[146:149], v171 offset:4608
	ds_read_b128 v[150:153], v171 offset:5760
	ds_read_b128 v[154:157], v171 offset:6912
	ds_read_b128 v[158:161], v171 offset:8064
	s_waitcnt lgkmcnt(7)
	global_store_dwordx4 v172, v[130:133], s[44:45] offset:0
	s_waitcnt lgkmcnt(6)
	global_store_dwordx4 v172, v[134:137], s[44:45] offset:1024
	s_waitcnt lgkmcnt(5)
	global_store_dwordx4 v172, v[138:141], s[44:45] offset:2048
	s_waitcnt lgkmcnt(4)
	global_store_dwordx4 v172, v[142:145], s[44:45] offset:3072
	s_waitcnt lgkmcnt(3)
; template <int EPI>
; DI void gemm_phase(const P& p, int l, const u16* __restrict__ A, const u16* __restrict__ Bt, int mpx, char* lds) {
;     ...
;           } else if (tr == 2) {
;             Tl[rowl * 72 + 0 * 16 + r] = f2h(v0);
;             Tl[rowl * 72 + 1 * 16 + r] = f2h(v1);
;             Tl[rowl * 72 + 2 * 16 + r] = f2h(v2);
;             Tl[rowl * 72 + 3 * 16 + r] = f2h(v3);
;           } else {
;             Tl[rowl * 72 + 0 * 16 + r] = (u16)u01;
;             Tl[rowl * 72 + 1 * 16 + r] = (u16)(u01 >> 16);
;             Tl[rowl * 72 + 2 * 16 + r] = (u16)u23;
;             Tl[rowl * 72 + 3 * 16 + r] = (u16)(u23 >> 16);
;           }
;         }
;       }
;       __builtin_amdgcn_fence(__ATOMIC_RELEASE, "wavefront");
;       u16* dh = (kind == 1) ? dst + hf * 64 : dst + (size_t)(hf * 64) * rstride;
; #pragma unroll
;       for (int i = 0; i < 8; ++i) {
;         const int c = lane + i * 64;
;         const int row = c >> 3, cc = c & 7;
;         uint4 v = *(const uint4*)&Tl[row * 72 + cc * 8];
;         *(uint4*)(dh + (size_t)row * rstride + cc * 8) = v;
;       }
	global_store_dwordx4 v172, v[146:149], s[62:63] offset:0
	s_waitcnt lgkmcnt(2)
	global_store_dwordx4 v172, v[150:153], s[62:63] offset:1024
	s_waitcnt lgkmcnt(1)
	global_store_dwordx4 v172, v[154:157], s[62:63] offset:2048
	s_waitcnt lgkmcnt(0)
	global_store_dwordx4 v172, v[158:161], s[62:63] offset:3072
	s_add_u32 s44, s44, 0x2000
	s_addc_u32 s45, s45, 0
	s_add_u32 s62, s62, 0x2000
	s_addc_u32 s63, s63, 0
	v_cvt_f16_f32_e32 v174, v62
	v_cvt_f16_f32_e32 v175, v58
	v_cvt_f16_f32_e32 v176, v54
	v_cvt_f16_f32_e32 v177, v50
	ds_write_b16 v170, v174 offset:0
	ds_write_b16 v170, v175 offset:32
	ds_write_b16 v170, v176 offset:64
	ds_write_b16 v170, v177 offset:96
	v_cvt_f16_f32_e32 v180, v63
	v_cvt_f16_f32_e32 v181, v59
	v_cvt_f16_f32_e32 v182, v55
	v_cvt_f16_f32_e32 v183, v51
	ds_write_b16 v170, v180 offset:144
	ds_write_b16 v170, v181 offset:176
	ds_write_b16 v170, v182 offset:208
	ds_write_b16 v170, v183 offset:240
	v_cvt_f16_f32_e32 v186, v64
	v_cvt_f16_f32_e32 v187, v60
	v_cvt_f16_f32_e32 v188, v56
	v_cvt_f16_f32_e32 v189, v52
	ds_write_b16 v170, v186 offset:288
	ds_write_b16 v170, v187 offset:320
	ds_write_b16 v170, v188 offset:352
	ds_write_b16 v170, v189 offset:384
	v_cvt_f16_f32_e32 v192, v65
	v_cvt_f16_f32_e32 v193, v61
	v_cvt_f16_f32_e32 v174, v57
	v_cvt_f16_f32_e32 v175, v53
	ds_write_b16 v170, v192 offset:432
	ds_write_b16 v170, v193 offset:464
	ds_write_b16 v170, v174 offset:496
	ds_write_b16 v170, v175 offset:528
	v_cvt_f16_f32_e32 v178, v46
	v_cvt_f16_f32_e32 v179, v42
	v_cvt_f16_f32_e32 v180, v38
	v_cvt_f16_f32_e32 v181, v34
	ds_write_b16 v170, v178 offset:2304
	ds_write_b16 v170, v179 offset:2336
	ds_write_b16 v170, v180 offset:2368
	ds_write_b16 v170, v181 offset:2400
	v_cvt_f16_f32_e32 v184, v47
	v_cvt_f16_f32_e32 v185, v43
	v_cvt_f16_f32_e32 v186, v39
	v_cvt_f16_f32_e32 v187, v35
	ds_write_b16 v170, v184 offset:2448
	ds_write_b16 v170, v185 offset:2480
	ds_write_b16 v170, v186 offset:2512
	ds_write_b16 v170, v187 offset:2544
	v_cvt_f16_f32_e32 v190, v48
	v_cvt_f16_f32_e32 v191, v44
	v_cvt_f16_f32_e32 v192, v40
	v_cvt_f16_f32_e32 v193, v36
	ds_write_b16 v170, v190 offset:2592
	ds_write_b16 v170, v191 offset:2624
	ds_write_b16 v170, v192 offset:2656
	ds_write_b16 v170, v193 offset:2688
	v_cvt_f16_f32_e32 v176, v49
	v_cvt_f16_f32_e32 v177, v45
	v_cvt_f16_f32_e32 v178, v41
	v_cvt_f16_f32_e32 v179, v37
	ds_write_b16 v170, v176 offset:2736
	ds_write_b16 v170, v177 offset:2768
	ds_write_b16 v170, v178 offset:2800
	ds_write_b16 v170, v179 offset:2832
	v_cvt_f16_f32_e32 v182, v30
	v_cvt_f16_f32_e32 v183, v26
	v_cvt_f16_f32_e32 v184, v22
	v_cvt_f16_f32_e32 v185, v18
	ds_write_b16 v170, v182 offset:4608
	ds_write_b16 v170, v183 offset:4640
	ds_write_b16 v170, v184 offset:4672
	ds_write_b16 v170, v185 offset:4704
	v_cvt_f16_f32_e32 v188, v31
	v_cvt_f16_f32_e32 v189, v27
	v_cvt_f16_f32_e32 v190, v23
	v_cvt_f16_f32_e32 v191, v19
	ds_write_b16 v170, v188 offset:4752
	ds_write_b16 v170, v189 offset:4784
	ds_write_b16 v170, v190 offset:4816
	ds_write_b16 v170, v191 offset:4848
	v_cvt_f16_f32_e32 v174, v32
	v_cvt_f16_f32_e32 v175, v28
	v_cvt_f16_f32_e32 v176, v24
	v_cvt_f16_f32_e32 v177, v20
	ds_write_b16 v170, v174 offset:4896
	ds_write_b16 v170, v175 offset:4928
	ds_write_b16 v170, v176 offset:4960
	ds_write_b16 v170, v177 offset:4992
	v_cvt_f16_f32_e32 v180, v33
	v_cvt_f16_f32_e32 v181, v29
	v_cvt_f16_f32_e32 v182, v25
	v_cvt_f16_f32_e32 v183, v21
	ds_write_b16 v170, v180 offset:5040
	ds_write_b16 v170, v181 offset:5072
	ds_write_b16 v170, v182 offset:5104
	ds_write_b16 v170, v183 offset:5136
	v_cvt_f16_f32_e32 v186, v166
	v_cvt_f16_f32_e32 v187, v162
	v_cvt_f16_f32_e32 v188, v2
	v_cvt_f16_f32_e32 v189, v6
	ds_write_b16 v170, v186 offset:6912
	ds_write_b16 v170, v187 offset:6944
	ds_write_b16 v170, v188 offset:6976
	ds_write_b16 v170, v189 offset:7008
	v_cvt_f16_f32_e32 v192, v167
	v_cvt_f16_f32_e32 v193, v163
	v_cvt_f16_f32_e32 v174, v3
	v_cvt_f16_f32_e32 v175, v7
	ds_write_b16 v170, v192 offset:7056
	ds_write_b16 v170, v193 offset:7088
	ds_write_b16 v170, v174 offset:7120
	ds_write_b16 v170, v175 offset:7152
	v_cvt_f16_f32_e32 v178, v168
	v_cvt_f16_f32_e32 v179, v164
	v_cvt_f16_f32_e32 v180, v4
	v_cvt_f16_f32_e32 v181, v8
	ds_write_b16 v170, v178 offset:7200
	ds_write_b16 v170, v179 offset:7232
	ds_write_b16 v170, v180 offset:7264
	ds_write_b16 v170, v181 offset:7296
	v_cvt_f16_f32_e32 v184, v169
	v_cvt_f16_f32_e32 v185, v165
	v_cvt_f16_f32_e32 v186, v5
	v_cvt_f16_f32_e32 v187, v9
	ds_write_b16 v170, v184 offset:7344
	ds_write_b16 v170, v185 offset:7376
	ds_write_b16 v170, v186 offset:7408
	ds_write_b16 v170, v187 offset:7440
	ds_read_b128 v[130:133], v171 offset:0
	ds_read_b128 v[134:137], v171 offset:1152
	ds_read_b128 v[138:141], v171 offset:2304
	ds_read_b128 v[142:145], v171 offset:3456
	ds_read_b128 v[146:149], v171 offset:4608
	ds_read_b128 v[150:153], v171 offset:5760
	ds_read_b128 v[154:157], v171 offset:6912
	ds_read_b128 v[158:161], v171 offset:8064
	s_waitcnt lgkmcnt(7)
	global_store_dwordx4 v172, v[130:133], s[44:45] offset:0
	s_waitcnt lgkmcnt(6)
	global_store_dwordx4 v172, v[134:137], s[44:45] offset:1024
	s_waitcnt lgkmcnt(5)
	global_store_dwordx4 v172, v[138:141], s[44:45] offset:2048
	s_waitcnt lgkmcnt(4)
	global_store_dwordx4 v172, v[142:145], s[44:45] offset:3072
	s_waitcnt lgkmcnt(3)
	global_store_dwordx4 v172, v[146:149], s[62:63] offset:0
	s_waitcnt lgkmcnt(2)
	global_store_dwordx4 v172, v[150:153], s[62:63] offset:1024
	s_waitcnt lgkmcnt(1)
	global_store_dwordx4 v172, v[154:157], s[62:63] offset:2048
	s_waitcnt lgkmcnt(0)
	global_store_dwordx4 v172, v[158:161], s[62:63] offset:3072
	s_branch .Lfe_done
; template <int EPI>
; DI void gemm_phase(const P& p, int l, const u16* __restrict__ A, const u16* __restrict__ Bt, int mpx, char* lds) {
;     ...
;     } else if (kind == 1) {
;       dst = slab_ptr(p, cb >> 6, b) + tokw;
;       rstride = T;
;     } else {
;       dst = slab_ptr(p, cb >> 6, b) + (size_t)tokw * 64;
;       rstride = 64;
;     }
;     ...
;           if (kind == 1) {
;             Tl[(0 * 16 + r) * 72 + rowl] = (u16)u01;
;             Tl[(1 * 16 + r) * 72 + rowl] = (u16)(u01 >> 16);
;             Tl[(2 * 16 + r) * 72 + rowl] = (u16)u23;
;             Tl[(3 * 16 + r) * 72 + rowl] = (u16)(u23 >> 16);
;           } else if (tr == 2) {
;             Tl[rowl * 72 + 0 * 16 + r] = f2h(v0);
;             Tl[rowl * 72 + 1 * 16 + r] = f2h(v1);
;             Tl[rowl * 72 + 2 * 16 + r] = f2h(v2);
;             Tl[rowl * 72 + 3 * 16 + r] = f2h(v3);
;           } else {
;             Tl[rowl * 72 + 0 * 16 + r] = (u16)u01;
;             Tl[rowl * 72 + 1 * 16 + r] = (u16)(u01 >> 16);
;             Tl[rowl * 72 + 2 * 16 + r] = (u16)u23;
;             Tl[rowl * 72 + 3 * 16 + r] = (u16)(u23 >> 16);
;           }
;         }
;       }
;       __builtin_amdgcn_fence(__ATOMIC_RELEASE, "wavefront");
;       u16* dh = (kind == 1) ? dst + hf * 64 : dst + (size_t)(hf * 64) * rstride;
; #pragma unroll
;       for (int i = 0; i < 8; ++i) {
;         const int c = lane + i * 64;
;         const int row = c >> 3, cc = c & 7;
;         uint4 v = *(const uint4*)&Tl[row * 72 + cc * 8];
;         *(uint4*)(dh + (size_t)row * rstride + cc * 8) = v;
;       }
.Lfe_kind1:
	s_sub_u32 s68, s66, 0x8000
	s_lshr_b32 s68, s68, 8
	s_lshr_b32 s69, s66, 11
	s_and_b32 s70, s66, 0x7ff
	s_cmp_eq_u32 s67, 0
	s_cselect_b32 s68, s69, s68
	s_cselect_b32 s69, s70, 0x800
	s_lshl_b32 s70, s42, 7
	s_add_i32 s69, s69, s70
	s_mul_i32 s70, s40, 0x2400
	s_add_i32 s70, s70, s78
	v_and_b32_e32 v173, 15, v226
	v_lshrrev_b32_e32 v0, 4, v226
	v_mul_u32_u24_e32 v170, 0x90, v173
	v_lshl_add_u32 v170, v0, 3, v170
	v_add_u32_e32 v170, s70, v170
	v_lshrrev_b32_e32 v0, 3, v226
	v_and_b32_e32 v173, 7, v226
	v_mul_u32_u24_e32 v171, 0x90, v0
	v_lshl_add_u32 v171, v173, 4, v171
	v_add_u32_e32 v171, s70, v171
	v_mul_u32_u24_e32 v172, 0x1200, v0
	v_lshl_add_u32 v172, v173, 4, v172
	s_lshl_b32 s70, s43, 4
	s_add_i32 s70, s70, s68
	s_mul_hi_u32 s71, s70, 0x48000
	s_mul_i32 s70, s70, 0x48000
	s_add_u32 s44, s18, s70
	s_addc_u32 s45, s19, s71
	s_lshl_b32 s70, s69, 1
	s_add_u32 s44, s44, s70
	s_addc_u32 s45, s45, 0
.Lfe_k1:
	s_mov_b64 s[62:63], s[44:45]
	v_cvt_pk_bf16_f32 v178, v126, v122
	v_cvt_pk_bf16_f32 v179, v118, v114
	ds_write_b16 v170, v178 offset:0
	ds_write_b16_d16_hi v170, v178 offset:2304
	ds_write_b16 v170, v179 offset:4608
	ds_write_b16_d16_hi v170, v179 offset:6912
	v_cvt_pk_bf16_f32 v184, v127, v123
	v_cvt_pk_bf16_f32 v185, v119, v115
	ds_write_b16 v170, v184 offset:2
	ds_write_b16_d16_hi v170, v184 offset:2306
	ds_write_b16 v170, v185 offset:4610
	ds_write_b16_d16_hi v170, v185 offset:6914
	v_cvt_pk_bf16_f32 v190, v128, v124
	v_cvt_pk_bf16_f32 v191, v120, v116
	ds_write_b16 v170, v190 offset:4
	ds_write_b16_d16_hi v170, v190 offset:2308
	ds_write_b16 v170, v191 offset:4612
	ds_write_b16_d16_hi v170, v191 offset:6916
	v_cvt_pk_bf16_f32 v176, v129, v125
	v_cvt_pk_bf16_f32 v177, v121, v117
	ds_write_b16 v170, v176 offset:6
	ds_write_b16_d16_hi v170, v176 offset:2310
	ds_write_b16 v170, v177 offset:4614
	ds_write_b16_d16_hi v170, v177 offset:6918
	v_cvt_pk_bf16_f32 v182, v110, v106
	v_cvt_pk_bf16_f32 v183, v102, v98
	ds_write_b16 v170, v182 offset:32
	ds_write_b16_d16_hi v170, v182 offset:2336
	ds_write_b16 v170, v183 offset:4640
	ds_write_b16_d16_hi v170, v183 offset:6944
	v_cvt_pk_bf16_f32 v188, v111, v107
	v_cvt_pk_bf16_f32 v189, v103, v99
	ds_write_b16 v170, v188 offset:34
	ds_write_b16_d16_hi v170, v188 offset:2338
	ds_write_b16 v170, v189 offset:4642
	ds_write_b16_d16_hi v170, v189 offset:6946
	v_cvt_pk_bf16_f32 v174, v112, v108
	v_cvt_pk_bf16_f32 v175, v104, v100
	ds_write_b16 v170, v174 offset:36
	ds_write_b16_d16_hi v170, v174 offset:2340
	ds_write_b16 v170, v175 offset:4644
	ds_write_b16_d16_hi v170, v175 offset:6948
	v_cvt_pk_bf16_f32 v180, v113, v109
	v_cvt_pk_bf16_f32 v181, v105, v101
	ds_write_b16 v170, v180 offset:38
	ds_write_b16_d16_hi v170, v180 offset:2342
	ds_write_b16 v170, v181 offset:4646
	ds_write_b16_d16_hi v170, v181 offset:6950
	v_cvt_pk_bf16_f32 v186, v94, v90
	v_cvt_pk_bf16_f32 v187, v86, v82
	ds_write_b16 v170, v186 offset:64
	ds_write_b16_d16_hi v170, v186 offset:2368
	ds_write_b16 v170, v187 offset:4672
	ds_write_b16_d16_hi v170, v187 offset:6976
	v_cvt_pk_bf16_f32 v192, v95, v91
	v_cvt_pk_bf16_f32 v193, v87, v83
	ds_write_b16 v170, v192 offset:66
	ds_write_b16_d16_hi v170, v192 offset:2370
	ds_write_b16 v170, v193 offset:4674
	ds_write_b16_d16_hi v170, v193 offset:6978
	v_cvt_pk_bf16_f32 v178, v96, v92
	v_cvt_pk_bf16_f32 v179, v88, v84
	ds_write_b16 v170, v178 offset:68
	ds_write_b16_d16_hi v170, v178 offset:2372
	ds_write_b16 v170, v179 offset:4676
	ds_write_b16_d16_hi v170, v179 offset:6980
	v_cvt_pk_bf16_f32 v184, v97, v93
	v_cvt_pk_bf16_f32 v185, v89, v85
	ds_write_b16 v170, v184 offset:70
	ds_write_b16_d16_hi v170, v184 offset:2374
	ds_write_b16 v170, v185 offset:4678
	ds_write_b16_d16_hi v170, v185 offset:6982
	v_cvt_pk_bf16_f32 v190, v78, v74
	v_cvt_pk_bf16_f32 v191, v70, v66
	ds_write_b16 v170, v190 offset:96
	ds_write_b16_d16_hi v170, v190 offset:2400
	ds_write_b16 v170, v191 offset:4704
	ds_write_b16_d16_hi v170, v191 offset:7008
	v_cvt_pk_bf16_f32 v176, v79, v75
	v_cvt_pk_bf16_f32 v177, v71, v67
	ds_write_b16 v170, v176 offset:98
	ds_write_b16_d16_hi v170, v176 offset:2402
	ds_write_b16 v170, v177 offset:4706
	ds_write_b16_d16_hi v170, v177 offset:7010
	v_cvt_pk_bf16_f32 v182, v80, v76
	v_cvt_pk_bf16_f32 v183, v72, v68
	ds_write_b16 v170, v182 offset:100
	ds_write_b16_d16_hi v170, v182 offset:2404
	ds_write_b16 v170, v183 offset:4708
	ds_write_b16_d16_hi v170, v183 offset:7012
	v_cvt_pk_bf16_f32 v188, v81, v77
	v_cvt_pk_bf16_f32 v189, v73, v69
	ds_write_b16 v170, v188 offset:102
	ds_write_b16_d16_hi v170, v188 offset:2406
	ds_write_b16 v170, v189 offset:4710
	ds_write_b16_d16_hi v170, v189 offset:7014
	ds_read_b128 v[130:133], v171 offset:0
	ds_read_b128 v[134:137], v171 offset:1152
	ds_read_b128 v[138:141], v171 offset:2304
	ds_read_b128 v[142:145], v171 offset:3456
	ds_read_b128 v[146:149], v171 offset:4608
	ds_read_b128 v[150:153], v171 offset:5760
	ds_read_b128 v[154:157], v171 offset:6912
	ds_read_b128 v[158:161], v171 offset:8064
	s_waitcnt lgkmcnt(7)
	global_store_dwordx4 v172, v[130:133], s[44:45]
	s_add_u32 s44, s44, 0x9000
	s_addc_u32 s45, s45, 0
	s_waitcnt lgkmcnt(6)
	global_store_dwordx4 v172, v[134:137], s[44:45]
	s_add_u32 s44, s44, 0x9000
	s_addc_u32 s45, s45, 0
	s_waitcnt lgkmcnt(5)
	global_store_dwordx4 v172, v[138:141], s[44:45]
	s_add_u32 s44, s44, 0x9000
	s_addc_u32 s45, s45, 0
	s_waitcnt lgkmcnt(4)
	global_store_dwordx4 v172, v[142:145], s[44:45]
	s_add_u32 s44, s44, 0x9000
	s_addc_u32 s45, s45, 0
	s_waitcnt lgkmcnt(3)
	global_store_dwordx4 v172, v[146:149], s[44:45]
	s_add_u32 s44, s44, 0x9000
	s_addc_u32 s45, s45, 0
	s_waitcnt lgkmcnt(2)
; template <int EPI>
; DI void gemm_phase(const P& p, int l, const u16* __restrict__ A, const u16* __restrict__ Bt, int mpx, char* lds) {
;     ...
;           if (kind == 1) {
;             Tl[(0 * 16 + r) * 72 + rowl] = (u16)u01;
;             Tl[(1 * 16 + r) * 72 + rowl] = (u16)(u01 >> 16);
;             Tl[(2 * 16 + r) * 72 + rowl] = (u16)u23;
;             Tl[(3 * 16 + r) * 72 + rowl] = (u16)(u23 >> 16);
;           } else if (tr == 2) {
;             Tl[rowl * 72 + 0 * 16 + r] = f2h(v0);
;             Tl[rowl * 72 + 1 * 16 + r] = f2h(v1);
;             Tl[rowl * 72 + 2 * 16 + r] = f2h(v2);
;             Tl[rowl * 72 + 3 * 16 + r] = f2h(v3);
;           } else {
;             Tl[rowl * 72 + 0 * 16 + r] = (u16)u01;
;             Tl[rowl * 72 + 1 * 16 + r] = (u16)(u01 >> 16);
;             Tl[rowl * 72 + 2 * 16 + r] = (u16)u23;
;             Tl[rowl * 72 + 3 * 16 + r] = (u16)(u23 >> 16);
;           }
;         }
;       }
;       __builtin_amdgcn_fence(__ATOMIC_RELEASE, "wavefront");
;       u16* dh = (kind == 1) ? dst + hf * 64 : dst + (size_t)(hf * 64) * rstride;
; #pragma unroll
;       for (int i = 0; i < 8; ++i) {
;         const int c = lane + i * 64;
;         const int row = c >> 3, cc = c & 7;
;         uint4 v = *(const uint4*)&Tl[row * 72 + cc * 8];
;         *(uint4*)(dh + (size_t)row * rstride + cc * 8) = v;
;       }
	global_store_dwordx4 v172, v[150:153], s[44:45]
	s_add_u32 s44, s44, 0x9000
	s_addc_u32 s45, s45, 0
	s_waitcnt lgkmcnt(1)
	global_store_dwordx4 v172, v[154:157], s[44:45]
	s_add_u32 s44, s44, 0x9000
	s_addc_u32 s45, s45, 0
	s_waitcnt lgkmcnt(0)
	global_store_dwordx4 v172, v[158:161], s[44:45]
	s_add_u32 s44, s62, 0x80
	s_addc_u32 s45, s63, 0
	v_cvt_pk_bf16_f32 v178, v62, v58
	v_cvt_pk_bf16_f32 v179, v54, v50
	ds_write_b16 v170, v178 offset:0
	ds_write_b16_d16_hi v170, v178 offset:2304
	ds_write_b16 v170, v179 offset:4608
	ds_write_b16_d16_hi v170, v179 offset:6912
	v_cvt_pk_bf16_f32 v184, v63, v59
	v_cvt_pk_bf16_f32 v185, v55, v51
	ds_write_b16 v170, v184 offset:2
	ds_write_b16_d16_hi v170, v184 offset:2306
	ds_write_b16 v170, v185 offset:4610
	ds_write_b16_d16_hi v170, v185 offset:6914
	v_cvt_pk_bf16_f32 v190, v64, v60
	v_cvt_pk_bf16_f32 v191, v56, v52
	ds_write_b16 v170, v190 offset:4
	ds_write_b16_d16_hi v170, v190 offset:2308
	ds_write_b16 v170, v191 offset:4612
	ds_write_b16_d16_hi v170, v191 offset:6916
	v_cvt_pk_bf16_f32 v176, v65, v61
	v_cvt_pk_bf16_f32 v177, v57, v53
	ds_write_b16 v170, v176 offset:6
	ds_write_b16_d16_hi v170, v176 offset:2310
	ds_write_b16 v170, v177 offset:4614
	ds_write_b16_d16_hi v170, v177 offset:6918
	v_cvt_pk_bf16_f32 v182, v46, v42
	v_cvt_pk_bf16_f32 v183, v38, v34
	ds_write_b16 v170, v182 offset:32
	ds_write_b16_d16_hi v170, v182 offset:2336
	ds_write_b16 v170, v183 offset:4640
	ds_write_b16_d16_hi v170, v183 offset:6944
	v_cvt_pk_bf16_f32 v188, v47, v43
	v_cvt_pk_bf16_f32 v189, v39, v35
	ds_write_b16 v170, v188 offset:34
	ds_write_b16_d16_hi v170, v188 offset:2338
	ds_write_b16 v170, v189 offset:4642
	ds_write_b16_d16_hi v170, v189 offset:6946
	v_cvt_pk_bf16_f32 v174, v48, v44
	v_cvt_pk_bf16_f32 v175, v40, v36
	ds_write_b16 v170, v174 offset:36
	ds_write_b16_d16_hi v170, v174 offset:2340
	ds_write_b16 v170, v175 offset:4644
	ds_write_b16_d16_hi v170, v175 offset:6948
	v_cvt_pk_bf16_f32 v180, v49, v45
	v_cvt_pk_bf16_f32 v181, v41, v37
	ds_write_b16 v170, v180 offset:38
	ds_write_b16_d16_hi v170, v180 offset:2342
	ds_write_b16 v170, v181 offset:4646
	ds_write_b16_d16_hi v170, v181 offset:6950
	v_cvt_pk_bf16_f32 v186, v30, v26
	v_cvt_pk_bf16_f32 v187, v22, v18
	ds_write_b16 v170, v186 offset:64
	ds_write_b16_d16_hi v170, v186 offset:2368
	ds_write_b16 v170, v187 offset:4672
	ds_write_b16_d16_hi v170, v187 offset:6976
	v_cvt_pk_bf16_f32 v192, v31, v27
	v_cvt_pk_bf16_f32 v193, v23, v19
	ds_write_b16 v170, v192 offset:66
	ds_write_b16_d16_hi v170, v192 offset:2370
	ds_write_b16 v170, v193 offset:4674
	ds_write_b16_d16_hi v170, v193 offset:6978
	v_cvt_pk_bf16_f32 v178, v32, v28
	v_cvt_pk_bf16_f32 v179, v24, v20
	ds_write_b16 v170, v178 offset:68
	ds_write_b16_d16_hi v170, v178 offset:2372
	ds_write_b16 v170, v179 offset:4676
	ds_write_b16_d16_hi v170, v179 offset:6980
	v_cvt_pk_bf16_f32 v184, v33, v29
	v_cvt_pk_bf16_f32 v185, v25, v21
	ds_write_b16 v170, v184 offset:70
	ds_write_b16_d16_hi v170, v184 offset:2374
	ds_write_b16 v170, v185 offset:4678
	ds_write_b16_d16_hi v170, v185 offset:6982
	v_cvt_pk_bf16_f32 v190, v166, v162
	v_cvt_pk_bf16_f32 v191, v2, v6
	ds_write_b16 v170, v190 offset:96
	ds_write_b16_d16_hi v170, v190 offset:2400
	ds_write_b16 v170, v191 offset:4704
	ds_write_b16_d16_hi v170, v191 offset:7008
	v_cvt_pk_bf16_f32 v176, v167, v163
	v_cvt_pk_bf16_f32 v177, v3, v7
	ds_write_b16 v170, v176 offset:98
	ds_write_b16_d16_hi v170, v176 offset:2402
	ds_write_b16 v170, v177 offset:4706
	ds_write_b16_d16_hi v170, v177 offset:7010
	v_cvt_pk_bf16_f32 v182, v168, v164
	v_cvt_pk_bf16_f32 v183, v4, v8
	ds_write_b16 v170, v182 offset:100
	ds_write_b16_d16_hi v170, v182 offset:2404
	ds_write_b16 v170, v183 offset:4708
	ds_write_b16_d16_hi v170, v183 offset:7012
	v_cvt_pk_bf16_f32 v188, v169, v165
	v_cvt_pk_bf16_f32 v189, v5, v9
	ds_write_b16 v170, v188 offset:102
	ds_write_b16_d16_hi v170, v188 offset:2406
	ds_write_b16 v170, v189 offset:4710
	ds_write_b16_d16_hi v170, v189 offset:7014
	ds_read_b128 v[130:133], v171 offset:0
	ds_read_b128 v[134:137], v171 offset:1152
	ds_read_b128 v[138:141], v171 offset:2304
	ds_read_b128 v[142:145], v171 offset:3456
	ds_read_b128 v[146:149], v171 offset:4608
	ds_read_b128 v[150:153], v171 offset:5760
	ds_read_b128 v[154:157], v171 offset:6912
	ds_read_b128 v[158:161], v171 offset:8064
	s_waitcnt lgkmcnt(7)
	global_store_dwordx4 v172, v[130:133], s[44:45]
	s_add_u32 s44, s44, 0x9000
	s_addc_u32 s45, s45, 0
	s_waitcnt lgkmcnt(6)
	global_store_dwordx4 v172, v[134:137], s[44:45]
	s_add_u32 s44, s44, 0x9000
	s_addc_u32 s45, s45, 0
	s_waitcnt lgkmcnt(5)
	global_store_dwordx4 v172, v[138:141], s[44:45]
	s_add_u32 s44, s44, 0x9000
	s_addc_u32 s45, s45, 0
	s_waitcnt lgkmcnt(4)
	global_store_dwordx4 v172, v[142:145], s[44:45]
	s_add_u32 s44, s44, 0x9000
	s_addc_u32 s45, s45, 0
	s_waitcnt lgkmcnt(3)
	global_store_dwordx4 v172, v[146:149], s[44:45]
	s_add_u32 s44, s44, 0x9000
	s_addc_u32 s45, s45, 0
	s_waitcnt lgkmcnt(2)
	global_store_dwordx4 v172, v[150:153], s[44:45]
	s_add_u32 s44, s44, 0x9000
	s_addc_u32 s45, s45, 0
	s_waitcnt lgkmcnt(1)
	global_store_dwordx4 v172, v[154:157], s[44:45]
	s_add_u32 s44, s44, 0x9000
	s_addc_u32 s45, s45, 0
	s_waitcnt lgkmcnt(0)
	global_store_dwordx4 v172, v[158:161], s[44:45]
	s_branch .Lfe_done
; DI float silu(float v) { return v * __builtin_amdgcn_rcpf(1.f + __builtin_amdgcn_exp2f(-1.4426950408889634f * v)); }
; template <int EPI>
; DI void gemm_phase(const P& p, int l, const u16* __restrict__ A, const u16* __restrict__ Bt, int mpx, char* lds) {
;     ...
;     if (kind == 2) {
;       dst = p.G + (size_t)(m0 + wm * 128) * 1024 + (cb - 2816);
;       rstride = 1024;
;     } else if (kind == 1) {
;       dst = slab_ptr(p, cb >> 6, b) + tokw;
;       rstride = T;
;     } else {
;       dst = slab_ptr(p, cb >> 6, b) + (size_t)tokw * 64;
;       rstride = 64;
;     }
; #pragma unroll
;     for (int hf = 0; hf < 2; ++hf) {
; #pragma unroll
;       for (int mi = 0; mi < 4; ++mi) {
; #pragma unroll
;         for (int j = 0; j < 4; ++j) {
;           float v0 = acc[hf * 4 + mi][0][j], v1 = acc[hf * 4 + mi][1][j], v2 = acc[hf * 4 + mi][2][j], v3 = acc[hf * 4 + mi][3][j];
;           const int rowl = mi * 16 + g * 4 + j;
;           const int s = tokw + hf * 64 + rowl;
;           if (tr == 1) {
;             v0 = silu(v0); v1 = silu(v1); v2 = silu(v2); v3 = silu(v3);
;     ...
;           } else {
;             Tl[rowl * 72 + 0 * 16 + r] = (u16)u01;
;             Tl[rowl * 72 + 1 * 16 + r] = (u16)(u01 >> 16);
;             Tl[rowl * 72 + 2 * 16 + r] = (u16)u23;
;             Tl[rowl * 72 + 3 * 16 + r] = (u16)(u23 >> 16);
;           }
;         }
;       }
;       __builtin_amdgcn_fence(__ATOMIC_RELEASE, "wavefront");
;       u16* dh = (kind == 1) ? dst + hf * 64 : dst + (size_t)(hf * 64) * rstride;
; #pragma unroll
;       for (int i = 0; i < 8; ++i) {
;         const int c = lane + i * 64;
;         const int row = c >> 3, cc = c & 7;
;         uint4 v = *(const uint4*)&Tl[row * 72 + cc * 8];
;         *(uint4*)(dh + (size_t)row * rstride + cc * 8) = v;
;       }
.Lfe_kind2:
	s_sub_u32 s68, s66, 0x8000
	s_lshr_b32 s68, s68, 8
	s_lshr_b32 s69, s66, 11
	s_and_b32 s70, s66, 0x7ff
	s_cmp_eq_u32 s67, 0
	s_cselect_b32 s68, s69, s68
	s_cselect_b32 s69, s70, 0x800
	s_lshl_b32 s70, s42, 7
	s_add_i32 s69, s69, s70
	s_mul_i32 s70, s40, 0x2400
	s_add_i32 s70, s70, s78
	v_and_b32_e32 v173, 15, v226
	v_lshrrev_b32_e32 v0, 4, v226
	v_mul_u32_u24_e32 v170, 0x240, v0
	v_lshl_add_u32 v170, v173, 1, v170
	v_add_u32_e32 v170, s70, v170
	v_lshrrev_b32_e32 v0, 3, v226
	v_and_b32_e32 v173, 7, v226
	v_mul_u32_u24_e32 v171, 0x90, v0
	v_lshl_add_u32 v171, v173, 4, v171
	v_add_u32_e32 v171, s70, v171
	v_lshlrev_b32_e32 v172, 11, v0
	v_lshl_add_u32 v172, v173, 4, v172
	v_readlane_b32 s44, v255, 28
	v_readlane_b32 s45, v255, 29
	s_lshl_b32 s70, s42, 7
	s_add_i32 s70, s70, s66
	s_mov_b32 s71, 0
	s_lshl_b64 s[70:71], s[70:71], 11
	s_add_u32 s44, s44, s70
	s_addc_u32 s45, s45, s71
	s_sub_i32 s70, s43, 44
	s_lshl_b32 s70, s70, 7
	s_add_u32 s44, s44, s70
	s_addc_u32 s45, s45, 0
.Lfe_k2:
	s_mov_b64 s[62:63], s[44:45]
	v_mul_f32_e32 v174, 0xbfb8aa3b, v126
	v_mul_f32_e32 v175, 0xbfb8aa3b, v122
	v_mul_f32_e32 v176, 0xbfb8aa3b, v118
	v_mul_f32_e32 v177, 0xbfb8aa3b, v114
	v_exp_f32_e32 v174, v174
	v_exp_f32_e32 v175, v175
	v_exp_f32_e32 v176, v176
	v_exp_f32_e32 v177, v177
	v_add_f32_e32 v174, 1.0, v174
	v_add_f32_e32 v175, 1.0, v175
	v_add_f32_e32 v176, 1.0, v176
	v_add_f32_e32 v177, 1.0, v177
	v_rcp_f32_e32 v174, v174
	v_rcp_f32_e32 v175, v175
	v_rcp_f32_e32 v176, v176
	v_rcp_f32_e32 v177, v177
	v_mul_f32_e32 v174, v126, v174
	v_mul_f32_e32 v175, v122, v175
	v_mul_f32_e32 v176, v118, v176
	v_mul_f32_e32 v177, v114, v177
	v_cvt_pk_bf16_f32 v178, v174, v175
	v_cvt_pk_bf16_f32 v179, v176, v177
	ds_write_b16 v170, v178 offset:0
	ds_write_b16_d16_hi v170, v178 offset:32
	ds_write_b16 v170, v179 offset:64
	ds_write_b16_d16_hi v170, v179 offset:96
	v_mul_f32_e32 v180, 0xbfb8aa3b, v127
	v_mul_f32_e32 v181, 0xbfb8aa3b, v123
	v_mul_f32_e32 v182, 0xbfb8aa3b, v119
	v_mul_f32_e32 v183, 0xbfb8aa3b, v115
	v_exp_f32_e32 v180, v180
	v_exp_f32_e32 v181, v181
	v_exp_f32_e32 v182, v182
	v_exp_f32_e32 v183, v183
	v_add_f32_e32 v180, 1.0, v180
	v_add_f32_e32 v181, 1.0, v181
	v_add_f32_e32 v182, 1.0, v182
	v_add_f32_e32 v183, 1.0, v183
	v_rcp_f32_e32 v180, v180
	v_rcp_f32_e32 v181, v181
	v_rcp_f32_e32 v182, v182
	v_rcp_f32_e32 v183, v183
	v_mul_f32_e32 v180, v127, v180
	v_mul_f32_e32 v181, v123, v181
	v_mul_f32_e32 v182, v119, v182
	v_mul_f32_e32 v183, v115, v183
	v_cvt_pk_bf16_f32 v184, v180, v181
	v_cvt_pk_bf16_f32 v185, v182, v183
	ds_write_b16 v170, v184 offset:144
	ds_write_b16_d16_hi v170, v184 offset:176
	ds_write_b16 v170, v185 offset:208
	ds_write_b16_d16_hi v170, v185 offset:240
	v_mul_f32_e32 v186, 0xbfb8aa3b, v128
	v_mul_f32_e32 v187, 0xbfb8aa3b, v124
	v_mul_f32_e32 v188, 0xbfb8aa3b, v120
	v_mul_f32_e32 v189, 0xbfb8aa3b, v116
	v_exp_f32_e32 v186, v186
	v_exp_f32_e32 v187, v187
	v_exp_f32_e32 v188, v188
	v_exp_f32_e32 v189, v189
	v_add_f32_e32 v186, 1.0, v186
	v_add_f32_e32 v187, 1.0, v187
	v_add_f32_e32 v188, 1.0, v188
	v_add_f32_e32 v189, 1.0, v189
	v_rcp_f32_e32 v186, v186
	v_rcp_f32_e32 v187, v187
	v_rcp_f32_e32 v188, v188
	v_rcp_f32_e32 v189, v189
	v_mul_f32_e32 v186, v128, v186
	v_mul_f32_e32 v187, v124, v187
	v_mul_f32_e32 v188, v120, v188
	v_mul_f32_e32 v189, v116, v189
	v_cvt_pk_bf16_f32 v190, v186, v187
	v_cvt_pk_bf16_f32 v191, v188, v189
	ds_write_b16 v170, v190 offset:288
	ds_write_b16_d16_hi v170, v190 offset:320
	ds_write_b16 v170, v191 offset:352
	ds_write_b16_d16_hi v170, v191 offset:384
	v_mul_f32_e32 v192, 0xbfb8aa3b, v129
	v_mul_f32_e32 v193, 0xbfb8aa3b, v125
	v_mul_f32_e32 v174, 0xbfb8aa3b, v121
	v_mul_f32_e32 v175, 0xbfb8aa3b, v117
	v_exp_f32_e32 v192, v192
	v_exp_f32_e32 v193, v193
	v_exp_f32_e32 v174, v174
	v_exp_f32_e32 v175, v175
	v_add_f32_e32 v192, 1.0, v192
	v_add_f32_e32 v193, 1.0, v193
	v_add_f32_e32 v174, 1.0, v174
	v_add_f32_e32 v175, 1.0, v175
	v_rcp_f32_e32 v192, v192
	v_rcp_f32_e32 v193, v193
	v_rcp_f32_e32 v174, v174
	v_rcp_f32_e32 v175, v175
	v_mul_f32_e32 v192, v129, v192
	v_mul_f32_e32 v193, v125, v193
	v_mul_f32_e32 v174, v121, v174
	v_mul_f32_e32 v175, v117, v175
	v_cvt_pk_bf16_f32 v176, v192, v193
	v_cvt_pk_bf16_f32 v177, v174, v175
	ds_write_b16 v170, v176 offset:432
	ds_write_b16_d16_hi v170, v176 offset:464
	ds_write_b16 v170, v177 offset:496
	ds_write_b16_d16_hi v170, v177 offset:528
	v_mul_f32_e32 v178, 0xbfb8aa3b, v110
	v_mul_f32_e32 v179, 0xbfb8aa3b, v106
	v_mul_f32_e32 v180, 0xbfb8aa3b, v102
	v_mul_f32_e32 v181, 0xbfb8aa3b, v98
	v_exp_f32_e32 v178, v178
	v_exp_f32_e32 v179, v179
	v_exp_f32_e32 v180, v180
	v_exp_f32_e32 v181, v181
	v_add_f32_e32 v178, 1.0, v178
	v_add_f32_e32 v179, 1.0, v179
	v_add_f32_e32 v180, 1.0, v180
	v_add_f32_e32 v181, 1.0, v181
	v_rcp_f32_e32 v178, v178
	v_rcp_f32_e32 v179, v179
	v_rcp_f32_e32 v180, v180
	v_rcp_f32_e32 v181, v181
	v_mul_f32_e32 v178, v110, v178
	v_mul_f32_e32 v179, v106, v179
	v_mul_f32_e32 v180, v102, v180
	v_mul_f32_e32 v181, v98, v181
	v_cvt_pk_bf16_f32 v182, v178, v179
	v_cvt_pk_bf16_f32 v183, v180, v181
	ds_write_b16 v170, v182 offset:2304
	ds_write_b16_d16_hi v170, v182 offset:2336
	ds_write_b16 v170, v183 offset:2368
	ds_write_b16_d16_hi v170, v183 offset:2400
	v_mul_f32_e32 v184, 0xbfb8aa3b, v111
	v_mul_f32_e32 v185, 0xbfb8aa3b, v107
	v_mul_f32_e32 v186, 0xbfb8aa3b, v103
	v_mul_f32_e32 v187, 0xbfb8aa3b, v99
	v_exp_f32_e32 v184, v184
	v_exp_f32_e32 v185, v185
	v_exp_f32_e32 v186, v186
	v_exp_f32_e32 v187, v187
	v_add_f32_e32 v184, 1.0, v184
	v_add_f32_e32 v185, 1.0, v185
	v_add_f32_e32 v186, 1.0, v186
	v_add_f32_e32 v187, 1.0, v187
	v_rcp_f32_e32 v184, v184
; DI float silu(float v) { return v * __builtin_amdgcn_rcpf(1.f + __builtin_amdgcn_exp2f(-1.4426950408889634f * v)); }
; template <int EPI>
; DI void gemm_phase(const P& p, int l, const u16* __restrict__ A, const u16* __restrict__ Bt, int mpx, char* lds) {
;     ...
;           if (tr == 1) {
;             v0 = silu(v0); v1 = silu(v1); v2 = silu(v2); v3 = silu(v3);
;     ...
;           } else {
;             Tl[rowl * 72 + 0 * 16 + r] = (u16)u01;
;             Tl[rowl * 72 + 1 * 16 + r] = (u16)(u01 >> 16);
;             Tl[rowl * 72 + 2 * 16 + r] = (u16)u23;
;             Tl[rowl * 72 + 3 * 16 + r] = (u16)(u23 >> 16);
;           }
;         }
;       }
;       __builtin_amdgcn_fence(__ATOMIC_RELEASE, "wavefront");
;       u16* dh = (kind == 1) ? dst + hf * 64 : dst + (size_t)(hf * 64) * rstride;
; #pragma unroll
;       for (int i = 0; i < 8; ++i) {
;         const int c = lane + i * 64;
;         const int row = c >> 3, cc = c & 7;
;         uint4 v = *(const uint4*)&Tl[row * 72 + cc * 8];
;         *(uint4*)(dh + (size_t)row * rstride + cc * 8) = v;
;       }
	v_rcp_f32_e32 v185, v185
	v_rcp_f32_e32 v186, v186
	v_rcp_f32_e32 v187, v187
	v_mul_f32_e32 v184, v111, v184
	v_mul_f32_e32 v185, v107, v185
	v_mul_f32_e32 v186, v103, v186
	v_mul_f32_e32 v187, v99, v187
	v_cvt_pk_bf16_f32 v188, v184, v185
	v_cvt_pk_bf16_f32 v189, v186, v187
	ds_write_b16 v170, v188 offset:2448
	ds_write_b16_d16_hi v170, v188 offset:2480
	ds_write_b16 v170, v189 offset:2512
	ds_write_b16_d16_hi v170, v189 offset:2544
	v_mul_f32_e32 v190, 0xbfb8aa3b, v112
	v_mul_f32_e32 v191, 0xbfb8aa3b, v108
	v_mul_f32_e32 v192, 0xbfb8aa3b, v104
	v_mul_f32_e32 v193, 0xbfb8aa3b, v100
	v_exp_f32_e32 v190, v190
	v_exp_f32_e32 v191, v191
	v_exp_f32_e32 v192, v192
	v_exp_f32_e32 v193, v193
	v_add_f32_e32 v190, 1.0, v190
	v_add_f32_e32 v191, 1.0, v191
	v_add_f32_e32 v192, 1.0, v192
	v_add_f32_e32 v193, 1.0, v193
	v_rcp_f32_e32 v190, v190
	v_rcp_f32_e32 v191, v191
	v_rcp_f32_e32 v192, v192
	v_rcp_f32_e32 v193, v193
	v_mul_f32_e32 v190, v112, v190
	v_mul_f32_e32 v191, v108, v191
	v_mul_f32_e32 v192, v104, v192
	v_mul_f32_e32 v193, v100, v193
	v_cvt_pk_bf16_f32 v174, v190, v191
	v_cvt_pk_bf16_f32 v175, v192, v193
	ds_write_b16 v170, v174 offset:2592
	ds_write_b16_d16_hi v170, v174 offset:2624
	ds_write_b16 v170, v175 offset:2656
	ds_write_b16_d16_hi v170, v175 offset:2688
	v_mul_f32_e32 v176, 0xbfb8aa3b, v113
	v_mul_f32_e32 v177, 0xbfb8aa3b, v109
	v_mul_f32_e32 v178, 0xbfb8aa3b, v105
	v_mul_f32_e32 v179, 0xbfb8aa3b, v101
	v_exp_f32_e32 v176, v176
	v_exp_f32_e32 v177, v177
	v_exp_f32_e32 v178, v178
	v_exp_f32_e32 v179, v179
	v_add_f32_e32 v176, 1.0, v176
	v_add_f32_e32 v177, 1.0, v177
	v_add_f32_e32 v178, 1.0, v178
	v_add_f32_e32 v179, 1.0, v179
	v_rcp_f32_e32 v176, v176
	v_rcp_f32_e32 v177, v177
	v_rcp_f32_e32 v178, v178
	v_rcp_f32_e32 v179, v179
	v_mul_f32_e32 v176, v113, v176
	v_mul_f32_e32 v177, v109, v177
	v_mul_f32_e32 v178, v105, v178
	v_mul_f32_e32 v179, v101, v179
	v_cvt_pk_bf16_f32 v180, v176, v177
	v_cvt_pk_bf16_f32 v181, v178, v179
	ds_write_b16 v170, v180 offset:2736
	ds_write_b16_d16_hi v170, v180 offset:2768
	ds_write_b16 v170, v181 offset:2800
	ds_write_b16_d16_hi v170, v181 offset:2832
	v_mul_f32_e32 v182, 0xbfb8aa3b, v94
	v_mul_f32_e32 v183, 0xbfb8aa3b, v90
	v_mul_f32_e32 v184, 0xbfb8aa3b, v86
	v_mul_f32_e32 v185, 0xbfb8aa3b, v82
	v_exp_f32_e32 v182, v182
	v_exp_f32_e32 v183, v183
	v_exp_f32_e32 v184, v184
	v_exp_f32_e32 v185, v185
	v_add_f32_e32 v182, 1.0, v182
	v_add_f32_e32 v183, 1.0, v183
	v_add_f32_e32 v184, 1.0, v184
	v_add_f32_e32 v185, 1.0, v185
	v_rcp_f32_e32 v182, v182
	v_rcp_f32_e32 v183, v183
	v_rcp_f32_e32 v184, v184
	v_rcp_f32_e32 v185, v185
	v_mul_f32_e32 v182, v94, v182
	v_mul_f32_e32 v183, v90, v183
	v_mul_f32_e32 v184, v86, v184
	v_mul_f32_e32 v185, v82, v185
	v_cvt_pk_bf16_f32 v186, v182, v183
	v_cvt_pk_bf16_f32 v187, v184, v185
	ds_write_b16 v170, v186 offset:4608
	ds_write_b16_d16_hi v170, v186 offset:4640
	ds_write_b16 v170, v187 offset:4672
	ds_write_b16_d16_hi v170, v187 offset:4704
	v_mul_f32_e32 v188, 0xbfb8aa3b, v95
	v_mul_f32_e32 v189, 0xbfb8aa3b, v91
	v_mul_f32_e32 v190, 0xbfb8aa3b, v87
	v_mul_f32_e32 v191, 0xbfb8aa3b, v83
	v_exp_f32_e32 v188, v188
	v_exp_f32_e32 v189, v189
	v_exp_f32_e32 v190, v190
	v_exp_f32_e32 v191, v191
	v_add_f32_e32 v188, 1.0, v188
	v_add_f32_e32 v189, 1.0, v189
	v_add_f32_e32 v190, 1.0, v190
	v_add_f32_e32 v191, 1.0, v191
	v_rcp_f32_e32 v188, v188
	v_rcp_f32_e32 v189, v189
	v_rcp_f32_e32 v190, v190
	v_rcp_f32_e32 v191, v191
	v_mul_f32_e32 v188, v95, v188
	v_mul_f32_e32 v189, v91, v189
	v_mul_f32_e32 v190, v87, v190
	v_mul_f32_e32 v191, v83, v191
	v_cvt_pk_bf16_f32 v192, v188, v189
	v_cvt_pk_bf16_f32 v193, v190, v191
	ds_write_b16 v170, v192 offset:4752
	ds_write_b16_d16_hi v170, v192 offset:4784
	ds_write_b16 v170, v193 offset:4816
	ds_write_b16_d16_hi v170, v193 offset:4848
	v_mul_f32_e32 v174, 0xbfb8aa3b, v96
	v_mul_f32_e32 v175, 0xbfb8aa3b, v92
	v_mul_f32_e32 v176, 0xbfb8aa3b, v88
	v_mul_f32_e32 v177, 0xbfb8aa3b, v84
	v_exp_f32_e32 v174, v174
	v_exp_f32_e32 v175, v175
	v_exp_f32_e32 v176, v176
	v_exp_f32_e32 v177, v177
	v_add_f32_e32 v174, 1.0, v174
	v_add_f32_e32 v175, 1.0, v175
	v_add_f32_e32 v176, 1.0, v176
	v_add_f32_e32 v177, 1.0, v177
	v_rcp_f32_e32 v174, v174
	v_rcp_f32_e32 v175, v175
	v_rcp_f32_e32 v176, v176
	v_rcp_f32_e32 v177, v177
	v_mul_f32_e32 v174, v96, v174
	v_mul_f32_e32 v175, v92, v175
	v_mul_f32_e32 v176, v88, v176
	v_mul_f32_e32 v177, v84, v177
	v_cvt_pk_bf16_f32 v178, v174, v175
	v_cvt_pk_bf16_f32 v179, v176, v177
	ds_write_b16 v170, v178 offset:4896
	ds_write_b16_d16_hi v170, v178 offset:4928
	ds_write_b16 v170, v179 offset:4960
	ds_write_b16_d16_hi v170, v179 offset:4992
	v_mul_f32_e32 v180, 0xbfb8aa3b, v97
	v_mul_f32_e32 v181, 0xbfb8aa3b, v93
	v_mul_f32_e32 v182, 0xbfb8aa3b, v89
	v_mul_f32_e32 v183, 0xbfb8aa3b, v85
	v_exp_f32_e32 v180, v180
	v_exp_f32_e32 v181, v181
	v_exp_f32_e32 v182, v182
	v_exp_f32_e32 v183, v183
	v_add_f32_e32 v180, 1.0, v180
	v_add_f32_e32 v181, 1.0, v181
	v_add_f32_e32 v182, 1.0, v182
	v_add_f32_e32 v183, 1.0, v183
	v_rcp_f32_e32 v180, v180
	v_rcp_f32_e32 v181, v181
	v_rcp_f32_e32 v182, v182
	v_rcp_f32_e32 v183, v183
	v_mul_f32_e32 v180, v97, v180
	v_mul_f32_e32 v181, v93, v181
	v_mul_f32_e32 v182, v89, v182
	v_mul_f32_e32 v183, v85, v183
	v_cvt_pk_bf16_f32 v184, v180, v181
	v_cvt_pk_bf16_f32 v185, v182, v183
	ds_write_b16 v170, v184 offset:5040
	ds_write_b16_d16_hi v170, v184 offset:5072
	ds_write_b16 v170, v185 offset:5104
	ds_write_b16_d16_hi v170, v185 offset:5136
	v_mul_f32_e32 v186, 0xbfb8aa3b, v78
	v_mul_f32_e32 v187, 0xbfb8aa3b, v74
	v_mul_f32_e32 v188, 0xbfb8aa3b, v70
	v_mul_f32_e32 v189, 0xbfb8aa3b, v66
; DI float silu(float v) { return v * __builtin_amdgcn_rcpf(1.f + __builtin_amdgcn_exp2f(-1.4426950408889634f * v)); }
; template <int EPI>
; DI void gemm_phase(const P& p, int l, const u16* __restrict__ A, const u16* __restrict__ Bt, int mpx, char* lds) {
;     ...
;           if (tr == 1) {
;             v0 = silu(v0); v1 = silu(v1); v2 = silu(v2); v3 = silu(v3);
;     ...
;           } else {
;             Tl[rowl * 72 + 0 * 16 + r] = (u16)u01;
;             Tl[rowl * 72 + 1 * 16 + r] = (u16)(u01 >> 16);
;             Tl[rowl * 72 + 2 * 16 + r] = (u16)u23;
;             Tl[rowl * 72 + 3 * 16 + r] = (u16)(u23 >> 16);
;           }
;         }
;       }
;       __builtin_amdgcn_fence(__ATOMIC_RELEASE, "wavefront");
;       u16* dh = (kind == 1) ? dst + hf * 64 : dst + (size_t)(hf * 64) * rstride;
; #pragma unroll
;       for (int i = 0; i < 8; ++i) {
;         const int c = lane + i * 64;
;         const int row = c >> 3, cc = c & 7;
;         uint4 v = *(const uint4*)&Tl[row * 72 + cc * 8];
;         *(uint4*)(dh + (size_t)row * rstride + cc * 8) = v;
;       }
	v_exp_f32_e32 v186, v186
	v_exp_f32_e32 v187, v187
	v_exp_f32_e32 v188, v188
	v_exp_f32_e32 v189, v189
	v_add_f32_e32 v186, 1.0, v186
	v_add_f32_e32 v187, 1.0, v187
	v_add_f32_e32 v188, 1.0, v188
	v_add_f32_e32 v189, 1.0, v189
	v_rcp_f32_e32 v186, v186
	v_rcp_f32_e32 v187, v187
	v_rcp_f32_e32 v188, v188
	v_rcp_f32_e32 v189, v189
	v_mul_f32_e32 v186, v78, v186
	v_mul_f32_e32 v187, v74, v187
	v_mul_f32_e32 v188, v70, v188
	v_mul_f32_e32 v189, v66, v189
	v_cvt_pk_bf16_f32 v190, v186, v187
	v_cvt_pk_bf16_f32 v191, v188, v189
	ds_write_b16 v170, v190 offset:6912
	ds_write_b16_d16_hi v170, v190 offset:6944
	ds_write_b16 v170, v191 offset:6976
	ds_write_b16_d16_hi v170, v191 offset:7008
	v_mul_f32_e32 v192, 0xbfb8aa3b, v79
	v_mul_f32_e32 v193, 0xbfb8aa3b, v75
	v_mul_f32_e32 v174, 0xbfb8aa3b, v71
	v_mul_f32_e32 v175, 0xbfb8aa3b, v67
	v_exp_f32_e32 v192, v192
	v_exp_f32_e32 v193, v193
	v_exp_f32_e32 v174, v174
	v_exp_f32_e32 v175, v175
	v_add_f32_e32 v192, 1.0, v192
	v_add_f32_e32 v193, 1.0, v193
	v_add_f32_e32 v174, 1.0, v174
	v_add_f32_e32 v175, 1.0, v175
	v_rcp_f32_e32 v192, v192
	v_rcp_f32_e32 v193, v193
	v_rcp_f32_e32 v174, v174
	v_rcp_f32_e32 v175, v175
	v_mul_f32_e32 v192, v79, v192
	v_mul_f32_e32 v193, v75, v193
	v_mul_f32_e32 v174, v71, v174
	v_mul_f32_e32 v175, v67, v175
	v_cvt_pk_bf16_f32 v176, v192, v193
	v_cvt_pk_bf16_f32 v177, v174, v175
	ds_write_b16 v170, v176 offset:7056
	ds_write_b16_d16_hi v170, v176 offset:7088
	ds_write_b16 v170, v177 offset:7120
	ds_write_b16_d16_hi v170, v177 offset:7152
	v_mul_f32_e32 v178, 0xbfb8aa3b, v80
	v_mul_f32_e32 v179, 0xbfb8aa3b, v76
	v_mul_f32_e32 v180, 0xbfb8aa3b, v72
	v_mul_f32_e32 v181, 0xbfb8aa3b, v68
	v_exp_f32_e32 v178, v178
	v_exp_f32_e32 v179, v179
	v_exp_f32_e32 v180, v180
	v_exp_f32_e32 v181, v181
	v_add_f32_e32 v178, 1.0, v178
	v_add_f32_e32 v179, 1.0, v179
	v_add_f32_e32 v180, 1.0, v180
	v_add_f32_e32 v181, 1.0, v181
	v_rcp_f32_e32 v178, v178
	v_rcp_f32_e32 v179, v179
	v_rcp_f32_e32 v180, v180
	v_rcp_f32_e32 v181, v181
	v_mul_f32_e32 v178, v80, v178
	v_mul_f32_e32 v179, v76, v179
	v_mul_f32_e32 v180, v72, v180
	v_mul_f32_e32 v181, v68, v181
	v_cvt_pk_bf16_f32 v182, v178, v179
	v_cvt_pk_bf16_f32 v183, v180, v181
	ds_write_b16 v170, v182 offset:7200
	ds_write_b16_d16_hi v170, v182 offset:7232
	ds_write_b16 v170, v183 offset:7264
	ds_write_b16_d16_hi v170, v183 offset:7296
	v_mul_f32_e32 v184, 0xbfb8aa3b, v81
	v_mul_f32_e32 v185, 0xbfb8aa3b, v77
	v_mul_f32_e32 v186, 0xbfb8aa3b, v73
	v_mul_f32_e32 v187, 0xbfb8aa3b, v69
	v_exp_f32_e32 v184, v184
	v_exp_f32_e32 v185, v185
	v_exp_f32_e32 v186, v186
	v_exp_f32_e32 v187, v187
	v_add_f32_e32 v184, 1.0, v184
	v_add_f32_e32 v185, 1.0, v185
	v_add_f32_e32 v186, 1.0, v186
	v_add_f32_e32 v187, 1.0, v187
	v_rcp_f32_e32 v184, v184
	v_rcp_f32_e32 v185, v185
	v_rcp_f32_e32 v186, v186
	v_rcp_f32_e32 v187, v187
	v_mul_f32_e32 v184, v81, v184
	v_mul_f32_e32 v185, v77, v185
	v_mul_f32_e32 v186, v73, v186
	v_mul_f32_e32 v187, v69, v187
	v_cvt_pk_bf16_f32 v188, v184, v185
	v_cvt_pk_bf16_f32 v189, v186, v187
	ds_write_b16 v170, v188 offset:7344
	ds_write_b16_d16_hi v170, v188 offset:7376
	ds_write_b16 v170, v189 offset:7408
	ds_write_b16_d16_hi v170, v189 offset:7440
	ds_read_b128 v[130:133], v171 offset:0
	ds_read_b128 v[134:137], v171 offset:1152
	ds_read_b128 v[138:141], v171 offset:2304
	ds_read_b128 v[142:145], v171 offset:3456
	ds_read_b128 v[146:149], v171 offset:4608
	ds_read_b128 v[150:153], v171 offset:5760
	ds_read_b128 v[154:157], v171 offset:6912
	ds_read_b128 v[158:161], v171 offset:8064
	s_waitcnt lgkmcnt(7)
	global_store_dwordx4 v172, v[130:133], s[44:45]
	s_add_u32 s44, s44, 0x4000
	s_addc_u32 s45, s45, 0
	s_waitcnt lgkmcnt(6)
	global_store_dwordx4 v172, v[134:137], s[44:45]
	s_add_u32 s44, s44, 0x4000
	s_addc_u32 s45, s45, 0
	s_waitcnt lgkmcnt(5)
	global_store_dwordx4 v172, v[138:141], s[44:45]
	s_add_u32 s44, s44, 0x4000
	s_addc_u32 s45, s45, 0
	s_waitcnt lgkmcnt(4)
	global_store_dwordx4 v172, v[142:145], s[44:45]
	s_add_u32 s44, s44, 0x4000
	s_addc_u32 s45, s45, 0
	s_waitcnt lgkmcnt(3)
	global_store_dwordx4 v172, v[146:149], s[44:45]
	s_add_u32 s44, s44, 0x4000
	s_addc_u32 s45, s45, 0
	s_waitcnt lgkmcnt(2)
	global_store_dwordx4 v172, v[150:153], s[44:45]
	s_add_u32 s44, s44, 0x4000
	s_addc_u32 s45, s45, 0
	s_waitcnt lgkmcnt(1)
	global_store_dwordx4 v172, v[154:157], s[44:45]
	s_add_u32 s44, s44, 0x4000
	s_addc_u32 s45, s45, 0
	s_waitcnt lgkmcnt(0)
; DI float silu(float v) { return v * __builtin_amdgcn_rcpf(1.f + __builtin_amdgcn_exp2f(-1.4426950408889634f * v)); }
; template <int EPI>
; DI void gemm_phase(const P& p, int l, const u16* __restrict__ A, const u16* __restrict__ Bt, int mpx, char* lds) {
;     ...
;           if (tr == 1) {
;             v0 = silu(v0); v1 = silu(v1); v2 = silu(v2); v3 = silu(v3);
;     ...
;           } else {
;             Tl[rowl * 72 + 0 * 16 + r] = (u16)u01;
;             Tl[rowl * 72 + 1 * 16 + r] = (u16)(u01 >> 16);
;             Tl[rowl * 72 + 2 * 16 + r] = (u16)u23;
;             Tl[rowl * 72 + 3 * 16 + r] = (u16)(u23 >> 16);
;           }
;         }
;       }
;       __builtin_amdgcn_fence(__ATOMIC_RELEASE, "wavefront");
;       u16* dh = (kind == 1) ? dst + hf * 64 : dst + (size_t)(hf * 64) * rstride;
; #pragma unroll
;       for (int i = 0; i < 8; ++i) {
;         const int c = lane + i * 64;
;         const int row = c >> 3, cc = c & 7;
;         uint4 v = *(const uint4*)&Tl[row * 72 + cc * 8];
;         *(uint4*)(dh + (size_t)row * rstride + cc * 8) = v;
;       }
	global_store_dwordx4 v172, v[158:161], s[44:45]
	s_add_u32 s44, s62, 0x20000
	s_addc_u32 s45, s63, 0
	v_mul_f32_e32 v174, 0xbfb8aa3b, v62
	v_mul_f32_e32 v175, 0xbfb8aa3b, v58
	v_mul_f32_e32 v176, 0xbfb8aa3b, v54
	v_mul_f32_e32 v177, 0xbfb8aa3b, v50
	v_exp_f32_e32 v174, v174
	v_exp_f32_e32 v175, v175
	v_exp_f32_e32 v176, v176
	v_exp_f32_e32 v177, v177
	v_add_f32_e32 v174, 1.0, v174
	v_add_f32_e32 v175, 1.0, v175
	v_add_f32_e32 v176, 1.0, v176
	v_add_f32_e32 v177, 1.0, v177
	v_rcp_f32_e32 v174, v174
	v_rcp_f32_e32 v175, v175
	v_rcp_f32_e32 v176, v176
	v_rcp_f32_e32 v177, v177
	v_mul_f32_e32 v174, v62, v174
	v_mul_f32_e32 v175, v58, v175
	v_mul_f32_e32 v176, v54, v176
	v_mul_f32_e32 v177, v50, v177
	v_cvt_pk_bf16_f32 v178, v174, v175
	v_cvt_pk_bf16_f32 v179, v176, v177
	ds_write_b16 v170, v178 offset:0
	ds_write_b16_d16_hi v170, v178 offset:32
	ds_write_b16 v170, v179 offset:64
	ds_write_b16_d16_hi v170, v179 offset:96
	v_mul_f32_e32 v180, 0xbfb8aa3b, v63
	v_mul_f32_e32 v181, 0xbfb8aa3b, v59
	v_mul_f32_e32 v182, 0xbfb8aa3b, v55
	v_mul_f32_e32 v183, 0xbfb8aa3b, v51
	v_exp_f32_e32 v180, v180
	v_exp_f32_e32 v181, v181
	v_exp_f32_e32 v182, v182
	v_exp_f32_e32 v183, v183
	v_add_f32_e32 v180, 1.0, v180
	v_add_f32_e32 v181, 1.0, v181
	v_add_f32_e32 v182, 1.0, v182
	v_add_f32_e32 v183, 1.0, v183
	v_rcp_f32_e32 v180, v180
	v_rcp_f32_e32 v181, v181
	v_rcp_f32_e32 v182, v182
	v_rcp_f32_e32 v183, v183
	v_mul_f32_e32 v180, v63, v180
	v_mul_f32_e32 v181, v59, v181
	v_mul_f32_e32 v182, v55, v182
	v_mul_f32_e32 v183, v51, v183
	v_cvt_pk_bf16_f32 v184, v180, v181
	v_cvt_pk_bf16_f32 v185, v182, v183
	ds_write_b16 v170, v184 offset:144
	ds_write_b16_d16_hi v170, v184 offset:176
	ds_write_b16 v170, v185 offset:208
	ds_write_b16_d16_hi v170, v185 offset:240
	v_mul_f32_e32 v186, 0xbfb8aa3b, v64
	v_mul_f32_e32 v187, 0xbfb8aa3b, v60
	v_mul_f32_e32 v188, 0xbfb8aa3b, v56
	v_mul_f32_e32 v189, 0xbfb8aa3b, v52
	v_exp_f32_e32 v186, v186
	v_exp_f32_e32 v187, v187
	v_exp_f32_e32 v188, v188
	v_exp_f32_e32 v189, v189
	v_add_f32_e32 v186, 1.0, v186
	v_add_f32_e32 v187, 1.0, v187
	v_add_f32_e32 v188, 1.0, v188
	v_add_f32_e32 v189, 1.0, v189
	v_rcp_f32_e32 v186, v186
	v_rcp_f32_e32 v187, v187
	v_rcp_f32_e32 v188, v188
	v_rcp_f32_e32 v189, v189
	v_mul_f32_e32 v186, v64, v186
	v_mul_f32_e32 v187, v60, v187
	v_mul_f32_e32 v188, v56, v188
	v_mul_f32_e32 v189, v52, v189
	v_cvt_pk_bf16_f32 v190, v186, v187
	v_cvt_pk_bf16_f32 v191, v188, v189
	ds_write_b16 v170, v190 offset:288
	ds_write_b16_d16_hi v170, v190 offset:320
	ds_write_b16 v170, v191 offset:352
	ds_write_b16_d16_hi v170, v191 offset:384
	v_mul_f32_e32 v192, 0xbfb8aa3b, v65
	v_mul_f32_e32 v193, 0xbfb8aa3b, v61
	v_mul_f32_e32 v174, 0xbfb8aa3b, v57
	v_mul_f32_e32 v175, 0xbfb8aa3b, v53
	v_exp_f32_e32 v192, v192
	v_exp_f32_e32 v193, v193
	v_exp_f32_e32 v174, v174
	v_exp_f32_e32 v175, v175
	v_add_f32_e32 v192, 1.0, v192
	v_add_f32_e32 v193, 1.0, v193
	v_add_f32_e32 v174, 1.0, v174
	v_add_f32_e32 v175, 1.0, v175
	v_rcp_f32_e32 v192, v192
	v_rcp_f32_e32 v193, v193
	v_rcp_f32_e32 v174, v174
	v_rcp_f32_e32 v175, v175
	v_mul_f32_e32 v192, v65, v192
	v_mul_f32_e32 v193, v61, v193
	v_mul_f32_e32 v174, v57, v174
	v_mul_f32_e32 v175, v53, v175
	v_cvt_pk_bf16_f32 v176, v192, v193
	v_cvt_pk_bf16_f32 v177, v174, v175
	ds_write_b16 v170, v176 offset:432
	ds_write_b16_d16_hi v170, v176 offset:464
	ds_write_b16 v170, v177 offset:496
	ds_write_b16_d16_hi v170, v177 offset:528
	v_mul_f32_e32 v178, 0xbfb8aa3b, v46
	v_mul_f32_e32 v179, 0xbfb8aa3b, v42
	v_mul_f32_e32 v180, 0xbfb8aa3b, v38
	v_mul_f32_e32 v181, 0xbfb8aa3b, v34
	v_exp_f32_e32 v178, v178
	v_exp_f32_e32 v179, v179
	v_exp_f32_e32 v180, v180
	v_exp_f32_e32 v181, v181
	v_add_f32_e32 v178, 1.0, v178
	v_add_f32_e32 v179, 1.0, v179
	v_add_f32_e32 v180, 1.0, v180
	v_add_f32_e32 v181, 1.0, v181
	v_rcp_f32_e32 v178, v178
	v_rcp_f32_e32 v179, v179
	v_rcp_f32_e32 v180, v180
	v_rcp_f32_e32 v181, v181
	v_mul_f32_e32 v178, v46, v178
	v_mul_f32_e32 v179, v42, v179
	v_mul_f32_e32 v180, v38, v180
	v_mul_f32_e32 v181, v34, v181
	v_cvt_pk_bf16_f32 v182, v178, v179
	v_cvt_pk_bf16_f32 v183, v180, v181
	ds_write_b16 v170, v182 offset:2304
	ds_write_b16_d16_hi v170, v182 offset:2336
	ds_write_b16 v170, v183 offset:2368
	ds_write_b16_d16_hi v170, v183 offset:2400
	v_mul_f32_e32 v184, 0xbfb8aa3b, v47
	v_mul_f32_e32 v185, 0xbfb8aa3b, v43
	v_mul_f32_e32 v186, 0xbfb8aa3b, v39
	v_mul_f32_e32 v187, 0xbfb8aa3b, v35
	v_exp_f32_e32 v184, v184
	v_exp_f32_e32 v185, v185
	v_exp_f32_e32 v186, v186
	v_exp_f32_e32 v187, v187
	v_add_f32_e32 v184, 1.0, v184
	v_add_f32_e32 v185, 1.0, v185
	v_add_f32_e32 v186, 1.0, v186
	v_add_f32_e32 v187, 1.0, v187
	v_rcp_f32_e32 v184, v184
	v_rcp_f32_e32 v185, v185
	v_rcp_f32_e32 v186, v186
	v_rcp_f32_e32 v187, v187
	v_mul_f32_e32 v184, v47, v184
	v_mul_f32_e32 v185, v43, v185
	v_mul_f32_e32 v186, v39, v186
	v_mul_f32_e32 v187, v35, v187
	v_cvt_pk_bf16_f32 v188, v184, v185
	v_cvt_pk_bf16_f32 v189, v186, v187
	ds_write_b16 v170, v188 offset:2448
	ds_write_b16_d16_hi v170, v188 offset:2480
	ds_write_b16 v170, v189 offset:2512
	ds_write_b16_d16_hi v170, v189 offset:2544
	v_mul_f32_e32 v190, 0xbfb8aa3b, v48
	v_mul_f32_e32 v191, 0xbfb8aa3b, v44
	v_mul_f32_e32 v192, 0xbfb8aa3b, v40
	v_mul_f32_e32 v193, 0xbfb8aa3b, v36
	v_exp_f32_e32 v190, v190
	v_exp_f32_e32 v191, v191
	v_exp_f32_e32 v192, v192
	v_exp_f32_e32 v193, v193
	v_add_f32_e32 v190, 1.0, v190
	v_add_f32_e32 v191, 1.0, v191
	v_add_f32_e32 v192, 1.0, v192
	v_add_f32_e32 v193, 1.0, v193
	v_rcp_f32_e32 v190, v190
	v_rcp_f32_e32 v191, v191
	v_rcp_f32_e32 v192, v192
	v_rcp_f32_e32 v193, v193
	v_mul_f32_e32 v190, v48, v190
	v_mul_f32_e32 v191, v44, v191
; DI float silu(float v) { return v * __builtin_amdgcn_rcpf(1.f + __builtin_amdgcn_exp2f(-1.4426950408889634f * v)); }
; template <int EPI>
; DI void gemm_phase(const P& p, int l, const u16* __restrict__ A, const u16* __restrict__ Bt, int mpx, char* lds) {
;     ...
;           if (tr == 1) {
;             v0 = silu(v0); v1 = silu(v1); v2 = silu(v2); v3 = silu(v3);
;     ...
;           } else {
;             Tl[rowl * 72 + 0 * 16 + r] = (u16)u01;
;             Tl[rowl * 72 + 1 * 16 + r] = (u16)(u01 >> 16);
;             Tl[rowl * 72 + 2 * 16 + r] = (u16)u23;
;             Tl[rowl * 72 + 3 * 16 + r] = (u16)(u23 >> 16);
;           }
;         }
;       }
;       __builtin_amdgcn_fence(__ATOMIC_RELEASE, "wavefront");
;       u16* dh = (kind == 1) ? dst + hf * 64 : dst + (size_t)(hf * 64) * rstride;
; #pragma unroll
;       for (int i = 0; i < 8; ++i) {
;         const int c = lane + i * 64;
;         const int row = c >> 3, cc = c & 7;
;         uint4 v = *(const uint4*)&Tl[row * 72 + cc * 8];
;         *(uint4*)(dh + (size_t)row * rstride + cc * 8) = v;
;       }
	v_mul_f32_e32 v192, v40, v192
	v_mul_f32_e32 v193, v36, v193
	v_cvt_pk_bf16_f32 v174, v190, v191
	v_cvt_pk_bf16_f32 v175, v192, v193
	ds_write_b16 v170, v174 offset:2592
	ds_write_b16_d16_hi v170, v174 offset:2624
	ds_write_b16 v170, v175 offset:2656
	ds_write_b16_d16_hi v170, v175 offset:2688
	v_mul_f32_e32 v176, 0xbfb8aa3b, v49
	v_mul_f32_e32 v177, 0xbfb8aa3b, v45
	v_mul_f32_e32 v178, 0xbfb8aa3b, v41
	v_mul_f32_e32 v179, 0xbfb8aa3b, v37
	v_exp_f32_e32 v176, v176
	v_exp_f32_e32 v177, v177
	v_exp_f32_e32 v178, v178
	v_exp_f32_e32 v179, v179
	v_add_f32_e32 v176, 1.0, v176
	v_add_f32_e32 v177, 1.0, v177
	v_add_f32_e32 v178, 1.0, v178
	v_add_f32_e32 v179, 1.0, v179
	v_rcp_f32_e32 v176, v176
	v_rcp_f32_e32 v177, v177
	v_rcp_f32_e32 v178, v178
	v_rcp_f32_e32 v179, v179
	v_mul_f32_e32 v176, v49, v176
	v_mul_f32_e32 v177, v45, v177
	v_mul_f32_e32 v178, v41, v178
	v_mul_f32_e32 v179, v37, v179
	v_cvt_pk_bf16_f32 v180, v176, v177
	v_cvt_pk_bf16_f32 v181, v178, v179
	ds_write_b16 v170, v180 offset:2736
	ds_write_b16_d16_hi v170, v180 offset:2768
	ds_write_b16 v170, v181 offset:2800
	ds_write_b16_d16_hi v170, v181 offset:2832
	v_mul_f32_e32 v182, 0xbfb8aa3b, v30
	v_mul_f32_e32 v183, 0xbfb8aa3b, v26
	v_mul_f32_e32 v184, 0xbfb8aa3b, v22
	v_mul_f32_e32 v185, 0xbfb8aa3b, v18
	v_exp_f32_e32 v182, v182
	v_exp_f32_e32 v183, v183
	v_exp_f32_e32 v184, v184
	v_exp_f32_e32 v185, v185
	v_add_f32_e32 v182, 1.0, v182
	v_add_f32_e32 v183, 1.0, v183
	v_add_f32_e32 v184, 1.0, v184
	v_add_f32_e32 v185, 1.0, v185
	v_rcp_f32_e32 v182, v182
	v_rcp_f32_e32 v183, v183
	v_rcp_f32_e32 v184, v184
	v_rcp_f32_e32 v185, v185
	v_mul_f32_e32 v182, v30, v182
	v_mul_f32_e32 v183, v26, v183
	v_mul_f32_e32 v184, v22, v184
	v_mul_f32_e32 v185, v18, v185
	v_cvt_pk_bf16_f32 v186, v182, v183
	v_cvt_pk_bf16_f32 v187, v184, v185
	ds_write_b16 v170, v186 offset:4608
	ds_write_b16_d16_hi v170, v186 offset:4640
	ds_write_b16 v170, v187 offset:4672
	ds_write_b16_d16_hi v170, v187 offset:4704
	v_mul_f32_e32 v188, 0xbfb8aa3b, v31
	v_mul_f32_e32 v189, 0xbfb8aa3b, v27
	v_mul_f32_e32 v190, 0xbfb8aa3b, v23
	v_mul_f32_e32 v191, 0xbfb8aa3b, v19
	v_exp_f32_e32 v188, v188
	v_exp_f32_e32 v189, v189
	v_exp_f32_e32 v190, v190
	v_exp_f32_e32 v191, v191
	v_add_f32_e32 v188, 1.0, v188
	v_add_f32_e32 v189, 1.0, v189
	v_add_f32_e32 v190, 1.0, v190
	v_add_f32_e32 v191, 1.0, v191
	v_rcp_f32_e32 v188, v188
	v_rcp_f32_e32 v189, v189
	v_rcp_f32_e32 v190, v190
	v_rcp_f32_e32 v191, v191
	v_mul_f32_e32 v188, v31, v188
	v_mul_f32_e32 v189, v27, v189
	v_mul_f32_e32 v190, v23, v190
	v_mul_f32_e32 v191, v19, v191
	v_cvt_pk_bf16_f32 v192, v188, v189
	v_cvt_pk_bf16_f32 v193, v190, v191
	ds_write_b16 v170, v192 offset:4752
	ds_write_b16_d16_hi v170, v192 offset:4784
	ds_write_b16 v170, v193 offset:4816
	ds_write_b16_d16_hi v170, v193 offset:4848
	v_mul_f32_e32 v174, 0xbfb8aa3b, v32
	v_mul_f32_e32 v175, 0xbfb8aa3b, v28
	v_mul_f32_e32 v176, 0xbfb8aa3b, v24
	v_mul_f32_e32 v177, 0xbfb8aa3b, v20
	v_exp_f32_e32 v174, v174
	v_exp_f32_e32 v175, v175
	v_exp_f32_e32 v176, v176
	v_exp_f32_e32 v177, v177
	v_add_f32_e32 v174, 1.0, v174
	v_add_f32_e32 v175, 1.0, v175
	v_add_f32_e32 v176, 1.0, v176
	v_add_f32_e32 v177, 1.0, v177
	v_rcp_f32_e32 v174, v174
	v_rcp_f32_e32 v175, v175
	v_rcp_f32_e32 v176, v176
	v_rcp_f32_e32 v177, v177
	v_mul_f32_e32 v174, v32, v174
	v_mul_f32_e32 v175, v28, v175
	v_mul_f32_e32 v176, v24, v176
	v_mul_f32_e32 v177, v20, v177
	v_cvt_pk_bf16_f32 v178, v174, v175
	v_cvt_pk_bf16_f32 v179, v176, v177
	ds_write_b16 v170, v178 offset:4896
	ds_write_b16_d16_hi v170, v178 offset:4928
	ds_write_b16 v170, v179 offset:4960
	ds_write_b16_d16_hi v170, v179 offset:4992
	v_mul_f32_e32 v180, 0xbfb8aa3b, v33
	v_mul_f32_e32 v181, 0xbfb8aa3b, v29
	v_mul_f32_e32 v182, 0xbfb8aa3b, v25
	v_mul_f32_e32 v183, 0xbfb8aa3b, v21
	v_exp_f32_e32 v180, v180
	v_exp_f32_e32 v181, v181
	v_exp_f32_e32 v182, v182
	v_exp_f32_e32 v183, v183
	v_add_f32_e32 v180, 1.0, v180
	v_add_f32_e32 v181, 1.0, v181
	v_add_f32_e32 v182, 1.0, v182
	v_add_f32_e32 v183, 1.0, v183
	v_rcp_f32_e32 v180, v180
	v_rcp_f32_e32 v181, v181
	v_rcp_f32_e32 v182, v182
	v_rcp_f32_e32 v183, v183
	v_mul_f32_e32 v180, v33, v180
	v_mul_f32_e32 v181, v29, v181
	v_mul_f32_e32 v182, v25, v182
	v_mul_f32_e32 v183, v21, v183
	v_cvt_pk_bf16_f32 v184, v180, v181
	v_cvt_pk_bf16_f32 v185, v182, v183
	ds_write_b16 v170, v184 offset:5040
	ds_write_b16_d16_hi v170, v184 offset:5072
	ds_write_b16 v170, v185 offset:5104
	ds_write_b16_d16_hi v170, v185 offset:5136
	v_mul_f32_e32 v186, 0xbfb8aa3b, v166
	v_mul_f32_e32 v187, 0xbfb8aa3b, v162
	v_mul_f32_e32 v188, 0xbfb8aa3b, v2
	v_mul_f32_e32 v189, 0xbfb8aa3b, v6
	v_exp_f32_e32 v186, v186
	v_exp_f32_e32 v187, v187
	v_exp_f32_e32 v188, v188
	v_exp_f32_e32 v189, v189
	v_add_f32_e32 v186, 1.0, v186
	v_add_f32_e32 v187, 1.0, v187
	v_add_f32_e32 v188, 1.0, v188
	v_add_f32_e32 v189, 1.0, v189
	v_rcp_f32_e32 v186, v186
	v_rcp_f32_e32 v187, v187
	v_rcp_f32_e32 v188, v188
	v_rcp_f32_e32 v189, v189
	v_mul_f32_e32 v186, v166, v186
	v_mul_f32_e32 v187, v162, v187
	v_mul_f32_e32 v188, v2, v188
	v_mul_f32_e32 v189, v6, v189
	v_cvt_pk_bf16_f32 v190, v186, v187
	v_cvt_pk_bf16_f32 v191, v188, v189
	ds_write_b16 v170, v190 offset:6912
	ds_write_b16_d16_hi v170, v190 offset:6944
	ds_write_b16 v170, v191 offset:6976
	ds_write_b16_d16_hi v170, v191 offset:7008
	v_mul_f32_e32 v192, 0xbfb8aa3b, v167
	v_mul_f32_e32 v193, 0xbfb8aa3b, v163
	v_mul_f32_e32 v174, 0xbfb8aa3b, v3
	v_mul_f32_e32 v175, 0xbfb8aa3b, v7
	v_exp_f32_e32 v192, v192
	v_exp_f32_e32 v193, v193
	v_exp_f32_e32 v174, v174
	v_exp_f32_e32 v175, v175
; template <int EPI>
; DI void gemm_phase(const P& p, int l, const u16* __restrict__ A, const u16* __restrict__ Bt, int mpx, char* lds) {
;     ...
;     if (cb >= 2816) { kind = 2; tr = 1; }
;     else if (cb < 256) tr = 1;
;     else if (cb < 512) tr = 0;
;     else if (cb < 1024) tr = 2;
;     else if (cb < 1408) { tr = 3; donorm = true; }
;     else if (cb < 1536) kind = 1;
;     else if (cb < 2048) tr = isctx ? 0 : 4;
;     else if (cb < 2304) kind = 1;
;     else if (cb < 2688) tr = isctx ? 0 : 3;
;     else kind = 1;
;     ...
;           } else {
;             Tl[rowl * 72 + 0 * 16 + r] = (u16)u01;
;             Tl[rowl * 72 + 1 * 16 + r] = (u16)(u01 >> 16);
;             Tl[rowl * 72 + 2 * 16 + r] = (u16)u23;
;             Tl[rowl * 72 + 3 * 16 + r] = (u16)(u23 >> 16);
;           }
;         }
;       }
;       __builtin_amdgcn_fence(__ATOMIC_RELEASE, "wavefront");
;       u16* dh = (kind == 1) ? dst + hf * 64 : dst + (size_t)(hf * 64) * rstride;
; #pragma unroll
;       for (int i = 0; i < 8; ++i) {
;         const int c = lane + i * 64;
;         const int row = c >> 3, cc = c & 7;
;         uint4 v = *(const uint4*)&Tl[row * 72 + cc * 8];
;         *(uint4*)(dh + (size_t)row * rstride + cc * 8) = v;
;       }
;       __builtin_amdgcn_fence(__ATOMIC_RELEASE, "wavefront");
;     }
;   }
;   if (!has_next) break;
;   t = tn; m0 = m1; n0 = n1; Ag = Agn; Bg = Bgn;
	v_add_f32_e32 v192, 1.0, v192
	v_add_f32_e32 v193, 1.0, v193
	v_add_f32_e32 v174, 1.0, v174
	v_add_f32_e32 v175, 1.0, v175
	v_rcp_f32_e32 v192, v192
	v_rcp_f32_e32 v193, v193
	v_rcp_f32_e32 v174, v174
	v_rcp_f32_e32 v175, v175
	v_mul_f32_e32 v192, v167, v192
	v_mul_f32_e32 v193, v163, v193
	v_mul_f32_e32 v174, v3, v174
	v_mul_f32_e32 v175, v7, v175
	v_cvt_pk_bf16_f32 v176, v192, v193
	v_cvt_pk_bf16_f32 v177, v174, v175
	ds_write_b16 v170, v176 offset:7056
	ds_write_b16_d16_hi v170, v176 offset:7088
	ds_write_b16 v170, v177 offset:7120
	ds_write_b16_d16_hi v170, v177 offset:7152
	v_mul_f32_e32 v178, 0xbfb8aa3b, v168
	v_mul_f32_e32 v179, 0xbfb8aa3b, v164
	v_mul_f32_e32 v180, 0xbfb8aa3b, v4
	v_mul_f32_e32 v181, 0xbfb8aa3b, v8
	v_exp_f32_e32 v178, v178
	v_exp_f32_e32 v179, v179
	v_exp_f32_e32 v180, v180
	v_exp_f32_e32 v181, v181
	v_add_f32_e32 v178, 1.0, v178
	v_add_f32_e32 v179, 1.0, v179
	v_add_f32_e32 v180, 1.0, v180
	v_add_f32_e32 v181, 1.0, v181
	v_rcp_f32_e32 v178, v178
	v_rcp_f32_e32 v179, v179
	v_rcp_f32_e32 v180, v180
	v_rcp_f32_e32 v181, v181
	v_mul_f32_e32 v178, v168, v178
	v_mul_f32_e32 v179, v164, v179
	v_mul_f32_e32 v180, v4, v180
	v_mul_f32_e32 v181, v8, v181
	v_cvt_pk_bf16_f32 v182, v178, v179
	v_cvt_pk_bf16_f32 v183, v180, v181
	ds_write_b16 v170, v182 offset:7200
	ds_write_b16_d16_hi v170, v182 offset:7232
	ds_write_b16 v170, v183 offset:7264
	ds_write_b16_d16_hi v170, v183 offset:7296
	v_mul_f32_e32 v184, 0xbfb8aa3b, v169
	v_mul_f32_e32 v185, 0xbfb8aa3b, v165
	v_mul_f32_e32 v186, 0xbfb8aa3b, v5
	v_mul_f32_e32 v187, 0xbfb8aa3b, v9
	v_exp_f32_e32 v184, v184
	v_exp_f32_e32 v185, v185
	v_exp_f32_e32 v186, v186
	v_exp_f32_e32 v187, v187
	v_add_f32_e32 v184, 1.0, v184
	v_add_f32_e32 v185, 1.0, v185
	v_add_f32_e32 v186, 1.0, v186
	v_add_f32_e32 v187, 1.0, v187
	v_rcp_f32_e32 v184, v184
	v_rcp_f32_e32 v185, v185
	v_rcp_f32_e32 v186, v186
	v_rcp_f32_e32 v187, v187
	v_mul_f32_e32 v184, v169, v184
	v_mul_f32_e32 v185, v165, v185
	v_mul_f32_e32 v186, v5, v186
	v_mul_f32_e32 v187, v9, v187
	v_cvt_pk_bf16_f32 v188, v184, v185
	v_cvt_pk_bf16_f32 v189, v186, v187
	ds_write_b16 v170, v188 offset:7344
	ds_write_b16_d16_hi v170, v188 offset:7376
	ds_write_b16 v170, v189 offset:7408
	ds_write_b16_d16_hi v170, v189 offset:7440
	ds_read_b128 v[130:133], v171 offset:0
	ds_read_b128 v[134:137], v171 offset:1152
	ds_read_b128 v[138:141], v171 offset:2304
	ds_read_b128 v[142:145], v171 offset:3456
	ds_read_b128 v[146:149], v171 offset:4608
	ds_read_b128 v[150:153], v171 offset:5760
	ds_read_b128 v[154:157], v171 offset:6912
	ds_read_b128 v[158:161], v171 offset:8064
	s_waitcnt lgkmcnt(7)
	global_store_dwordx4 v172, v[130:133], s[44:45]
	s_add_u32 s44, s44, 0x4000
	s_addc_u32 s45, s45, 0
	s_waitcnt lgkmcnt(6)
	global_store_dwordx4 v172, v[134:137], s[44:45]
	s_add_u32 s44, s44, 0x4000
	s_addc_u32 s45, s45, 0
	s_waitcnt lgkmcnt(5)
	global_store_dwordx4 v172, v[138:141], s[44:45]
	s_add_u32 s44, s44, 0x4000
	s_addc_u32 s45, s45, 0
	s_waitcnt lgkmcnt(4)
	global_store_dwordx4 v172, v[142:145], s[44:45]
	s_add_u32 s44, s44, 0x4000
	s_addc_u32 s45, s45, 0
	s_waitcnt lgkmcnt(3)
	global_store_dwordx4 v172, v[146:149], s[44:45]
	s_add_u32 s44, s44, 0x4000
	s_addc_u32 s45, s45, 0
	s_waitcnt lgkmcnt(2)
	global_store_dwordx4 v172, v[150:153], s[44:45]
	s_add_u32 s44, s44, 0x4000
	s_addc_u32 s45, s45, 0
	s_waitcnt lgkmcnt(1)
	global_store_dwordx4 v172, v[154:157], s[44:45]
	s_add_u32 s44, s44, 0x4000
	s_addc_u32 s45, s45, 0
	s_waitcnt lgkmcnt(0)
	global_store_dwordx4 v172, v[158:161], s[44:45]
	s_branch .Lfe_done
.Lfe_done:
	v_mov_b32_e32 v236, 0x358637bd
	s_and_b64 vcc, exec, s[54:55]
	s_mov_b32 s46, s51
	s_mov_b32 s66, s56
	s_mov_b64 s[0:1], s[60:61]
	s_mov_b64 s[40:41], s[58:59]
	s_cbranch_vccnz .LBB0_811
	s_branch .LBB0_79
.Lfe_slow:
	v_mov_b32_e32 v148, v195
	s_movk_i32 s0, 0xf5ff
	v_and_b32_e32 v0, 0xc0, v148
	v_add_u32_e32 v140, s46, v0
	v_mov_b32_e32 v0, 0x8000
	v_sub_co_u32_e32 v137, vcc, s66, v0
	v_add_u32_e32 v0, 0xfffff500, v140
	v_cmp_lt_u32_e64 s[40:41], s0, v0
	v_mov_b32_e32 v147, 1
	s_mov_b64 s[64:65], 0
	s_mov_b64 s[0:1], 0
	s_mov_b64 s[42:43], exec
	s_and_b64 s[40:41], s[42:43], s[40:41]
	v_mov_b32_e32 v236, 0x358637bd
	s_mov_b64 exec, s[40:41]
	s_cbranch_execz .LBB0_97
	s_movk_i32 s0, 0x1ff
	v_cmp_lt_u32_e64 s[40:41], s0, v140
	v_mov_b32_e32 v147, 0
	s_mov_b64 s[46:47], 0
	s_mov_b64 s[44:45], 0
	s_and_saveexec_b64 s[0:1], s[40:41]
	s_cbranch_execz .LBB0_96
	s_movk_i32 s2, 0x3ff
	v_cmp_lt_u32_e64 s[40:41], s2, v140
	v_mov_b32_e32 v147, 2
	s_mov_b64 s[62:63], 0
	s_and_saveexec_b64 s[44:45], s[40:41]
	s_cbranch_execz .LBB0_95
	s_movk_i32 s2, 0x57f
	v_cmp_lt_u32_e64 s[40:41], s2, v140
	s_mov_b64 s[48:49], 0
	v_mov_b32_e32 v147, 3
	s_mov_b64 s[62:63], -1
	s_and_saveexec_b64 s[46:47], s[40:41]
	s_cbranch_execz .LBB0_94
	s_movk_i32 s2, 0x5ff
	v_cmp_lt_u32_e64 s[40:41], s2, v140
	s_mov_b64 s[64:65], -1
	v_mov_b32_e32 v147, 0
	s_and_saveexec_b64 s[48:49], s[40:41]
	s_cbranch_execz .LBB0_93
	s_movk_i32 s2, 0x7ff
	v_cmp_lt_u32_e64 s[40:41], s2, v140
	s_and_saveexec_b64 s[64:65], s[40:41]
	s_xor_b64 s[40:41], exec, s[64:65]
	s_and_b64 s[62:63], vcc, exec
	s_cselect_b32 s2, 3, 0
	v_add_u32_e32 v0, 0xfffff580, v140
	v_mov_b32_e32 v10, s2
	s_movk_i32 s2, 0xfe80
	v_cmp_gt_u32_e64 s[62:63], s2, v0
	s_nop 1
	v_cndmask_b32_e64 v147, v10, 0, s[62:63]
	s_andn2_saveexec_b64 s[40:41], s[40:41]
	s_and_b64 s[64:65], vcc, exec
	s_cselect_b32 s2, 4, 0
	v_mov_b32_e32 v147, s2
	s_andn2_b64 s[62:63], s[62:63], exec
	s_or_b64 exec, exec, s[40:41]
	s_orn2_b64 s[64:65], s[62:63], exec
